# LN epilogue: statistics-slot loads issued together (one device-scope round trip instead of three); gamma/beta loads hoisted so per-iteration vmcnt(0) store drains disappear; on top of residual-load pi
# baseline (speedup 1.0000x reference)
.LBB0_469:
	s_waitcnt vmcnt(0) lgkmcnt(0)
	s_barrier
	s_and_saveexec_b64 s[6:7], s[4:5]
	s_cbranch_execz .LBB0_471
	v_readlane_b32 s0, v252, 61
	v_lshlrev_b64 v[0:1], 5, v[0:1]
	v_readlane_b32 s1, v252, 62
	s_nop 1
	v_lshl_add_u64 v[0:1], s[0:1], 0, v[0:1]
	global_load_dwordx2 v[132:133], v[0:1], off sc1
	global_load_dwordx2 v[134:135], v[0:1], off offset:8 sc1
	global_load_dwordx2 v[244:245], v[0:1], off offset:16 sc1
	global_load_dwordx2 v[246:247], v[0:1], off offset:24 sc1
	s_mov_b32 s0, 0xf800000
	s_waitcnt vmcnt(3)
	v_add_f32_e32 v136, 0, v132
	s_waitcnt vmcnt(2)
	v_add_f32_e32 v138, v136, v134
	s_waitcnt vmcnt(1)
	v_mov_b32_e32 v136, v244
	v_mov_b32_e32 v137, v245
	v_add_f32_e32 v138, v138, v136
	s_waitcnt vmcnt(0)
	v_mov_b32_e32 v0, v246
	v_mov_b32_e32 v1, v247
	v_add_f32_e32 v139, v138, v0
	v_fmamk_f32 v132, v139, 0xbe800000, v132
	v_mul_f32_e32 v140, 0x43800000, v132
	v_fmac_f32_e32 v133, v132, v140
	v_add_f32_e32 v132, 0, v133
	v_fmamk_f32 v133, v139, 0xbe800000, v134
	v_mul_f32_e32 v134, 0x43800000, v133
	v_fmac_f32_e32 v135, v133, v134
	v_fmamk_f32 v133, v139, 0xbe800000, v136
	v_mul_f32_e32 v134, 0x43800000, v133
	v_fmamk_f32 v0, v139, 0xbe800000, v0
	v_add_f32_e32 v132, v135, v132
	v_fmac_f32_e32 v137, v133, v134
	v_mul_f32_e32 v133, 0x43800000, v0
	v_add_f32_e32 v132, v137, v132
	v_fmac_f32_e32 v1, v0, v133
	v_add_f32_e32 v0, v1, v132
	v_fmamk_f32 v0, v0, 0x3a800000, v173
	v_cmp_gt_f32_e32 vcc, s0, v0
	v_mul_f32_e32 v1, 0x4f800000, v0
	v_mul_f32_e32 v138, 0x3e800000, v139
	v_cndmask_b32_e32 v0, v0, v1, vcc
	v_sqrt_f32_e32 v1, v0
	s_nop 0
	v_add_u32_e32 v132, -1, v1
	v_fma_f32 v133, -v132, v1, v0
	v_cmp_ge_f32_e64 s[0:1], 0, v133
	v_add_u32_e32 v133, 1, v1
	s_nop 0
	v_cndmask_b32_e64 v132, v1, v132, s[0:1]
	v_fma_f32 v1, -v133, v1, v0
	v_cmp_lt_f32_e64 s[0:1], 0, v1
	s_nop 1
	v_cndmask_b32_e64 v1, v132, v133, s[0:1]
	v_mul_f32_e32 v132, 0x37800000, v1
	v_cndmask_b32_e32 v1, v1, v132, vcc
	v_cmp_class_f32_e32 vcc, v0, v174
	s_nop 1
	v_cndmask_b32_e32 v0, v1, v0, vcc
	v_div_scale_f32 v1, s[0:1], v0, v0, 1.0
	v_rcp_f32_e32 v132, v1
	s_nop 0
	v_fma_f32 v133, -v1, v132, 1.0
	v_fmac_f32_e32 v132, v133, v132
	v_div_scale_f32 v133, vcc, 1.0, v0, 1.0
	v_mul_f32_e32 v134, v133, v132
	v_fma_f32 v135, -v1, v134, v133
	v_fmac_f32_e32 v134, v135, v132
	v_fma_f32 v1, -v1, v134, v133
	v_div_fmas_f32 v1, v1, v132, v134
	v_div_fixup_f32 v139, v1, v0, 1.0
	v_lshl_add_u32 v0, v2, 3, 0
	ds_write_b64 v0, v[138:139] offset:8192

.LBB0_494:
	v_ashrrev_i32_e32 v165, 31, v164
	v_lshlrev_b64 v[132:133], 2, v[164:165]
	v_lshl_add_u64 v[0:1], s[6:7], 0, v[132:133]
	v_lshl_add_u64 v[166:167], s[4:5], 0, v[132:133]
	global_load_dwordx4 v[148:151], v[0:1], off
	global_load_dwordx4 v[152:155], v[166:167], off
	global_load_dwordx4 v[200:203], v[0:1], off offset:64
	global_load_dwordx4 v[204:207], v[166:167], off offset:64
	global_load_dwordx4 v[208:211], v[0:1], off offset:512
	global_load_dwordx4 v[212:215], v[166:167], off offset:512
	global_load_dwordx4 v[216:219], v[0:1], off offset:576
	global_load_dwordx4 v[220:223], v[166:167], off offset:576
	s_lshl_b32 s0, s80, 9
	s_add_i32 s0, s0, 0
	v_lshl_add_u32 v132, v176, 3, s0
	v_lshlrev_b32_e32 v2, 10, v176
	v_add_u32_e32 v132, 0x2000, v132
	v_lshl_add_u32 v165, s87, 18, v164
	v_lshl_or_b32 v177, s80, 16, v2
	v_readlane_b32 s0, v253, 15
	ds_read2_b64 v[144:147], v132 offset1:16
	ds_read2_b64 v[140:143], v132 offset0:32 offset1:48
	ds_read2_b64 v[136:139], v132 offset0:128 offset1:144
	ds_read2_b64 v[132:135], v132 offset0:160 offset1:176
	v_add_u32_e32 v2, v165, v177
	v_or_b32_e32 v179, 0x4000, v177
	v_readlane_b32 s1, v253, 16
	v_or_b32_e32 v178, 0x8000, v177
	s_waitcnt lgkmcnt(3)
	v_sub_f32_e32 v31, v31, v144
	v_lshl_add_u64 v[180:181], v[2:3], 1, s[0:1]
	v_add_u32_e32 v2, v165, v179
	v_sub_f32_e32 v30, v30, v144
	v_sub_f32_e32 v29, v29, v144
	v_sub_f32_e32 v28, v28, v144
	v_or_b32_e32 v176, 0xc000, v177
	v_lshl_add_u64 v[182:183], v[2:3], 1, s[0:1]
	v_add_u32_e32 v2, v165, v178
	v_sub_f32_e32 v35, v35, v146
	v_sub_f32_e32 v34, v34, v146
	v_sub_f32_e32 v33, v33, v146
	v_sub_f32_e32 v32, v32, v146
	s_waitcnt lgkmcnt(2)
	v_sub_f32_e32 v63, v63, v140
	v_sub_f32_e32 v62, v62, v140
	v_sub_f32_e32 v61, v61, v140
	v_sub_f32_e32 v60, v60, v140
	v_pk_mul_f32 v[28:29], v[144:145], v[28:29] op_sel:[1,0]
	v_pk_mul_f32 v[30:31], v[144:145], v[30:31] op_sel:[1,0]
	v_lshl_add_u64 v[184:185], v[2:3], 1, s[0:1]
	v_add_u32_e32 v2, v165, v176
	v_pk_mul_f32 v[32:33], v[146:147], v[32:33] op_sel:[1,0]
	v_pk_mul_f32 v[34:35], v[146:147], v[34:35] op_sel:[1,0]
	v_pk_mul_f32 v[60:61], v[140:141], v[60:61] op_sel:[1,0]
	v_pk_mul_f32 v[62:63], v[140:141], v[62:63] op_sel:[1,0]
	v_lshl_add_u64 v[186:187], v[2:3], 1, s[0:1]
	v_sub_f32_e32 v67, v67, v142
	v_sub_f32_e32 v66, v66, v142
	v_sub_f32_e32 v65, v65, v142
	v_sub_f32_e32 v64, v64, v142
	s_waitcnt lgkmcnt(1)
	v_sub_f32_e32 v95, v95, v136
	v_sub_f32_e32 v94, v94, v136
	v_pk_mul_f32 v[64:65], v[142:143], v[64:65] op_sel:[1,0]
	v_pk_mul_f32 v[66:67], v[142:143], v[66:67] op_sel:[1,0]
	v_add_u32_e32 v164, 0x20000, v177
	v_sub_f32_e32 v23, v23, v144
	v_sub_f32_e32 v22, v22, v144
	v_sub_f32_e32 v21, v21, v144
	v_sub_f32_e32 v20, v20, v144
	v_pk_mul_f32 v[20:21], v[144:145], v[20:21] op_sel:[1,0]
	v_pk_mul_f32 v[22:23], v[144:145], v[22:23] op_sel:[1,0]
	v_sub_f32_e32 v27, v27, v146
	v_sub_f32_e32 v26, v26, v146
	v_sub_f32_e32 v25, v25, v146
	v_sub_f32_e32 v24, v24, v146
	v_pk_mul_f32 v[24:25], v[146:147], v[24:25] op_sel:[1,0]
	v_pk_mul_f32 v[26:27], v[146:147], v[26:27] op_sel:[1,0]
	v_sub_f32_e32 v15, v15, v144
	v_sub_f32_e32 v14, v14, v144
	v_sub_f32_e32 v13, v13, v144
	v_sub_f32_e32 v12, v12, v144
	v_pk_mul_f32 v[12:13], v[144:145], v[12:13] op_sel:[1,0]
	v_pk_mul_f32 v[14:15], v[144:145], v[14:15] op_sel:[1,0]
	v_sub_f32_e32 v19, v19, v146
	v_sub_f32_e32 v18, v18, v146
	v_sub_f32_e32 v17, v17, v146
	v_sub_f32_e32 v16, v16, v146
	v_pk_mul_f32 v[16:17], v[146:147], v[16:17] op_sel:[1,0]
	v_pk_mul_f32 v[18:19], v[146:147], v[18:19] op_sel:[1,0]
	s_waitcnt vmcnt(3)
	v_sub_f32_e32 v5, v5, v144
	v_sub_f32_e32 v4, v4, v144
	v_pk_mul_f32 v[4:5], v[144:145], v[4:5] op_sel:[1,0]
	s_waitcnt vmcnt(2)
	v_sub_f32_e32 v9, v9, v146
	v_sub_f32_e32 v8, v8, v146
	v_pk_mul_f32 v[8:9], v[146:147], v[8:9] op_sel:[1,0]
	s_waitcnt vmcnt(0)
	v_pk_fma_f32 v[30:31], v[30:31], v[150:151], v[154:155]
	v_pk_fma_f32 v[28:29], v[28:29], v[148:149], v[152:153]
	v_pk_fma_f32 v[34:35], v[34:35], v[150:151], v[154:155]
	v_pk_fma_f32 v[32:33], v[32:33], v[148:149], v[152:153]
	v_pk_fma_f32 v[62:63], v[62:63], v[150:151], v[154:155]
	v_pk_fma_f32 v[60:61], v[60:61], v[148:149], v[152:153]
	v_cvt_f16_f32_e32 v2, v28
	v_cvt_f16_f32_sdwa v28, v29 dst_sel:WORD_1 dst_unused:UNUSED_PAD src0_sel:DWORD
	v_cvt_f16_f32_e32 v29, v30
	v_cvt_f16_f32_sdwa v30, v31 dst_sel:WORD_1 dst_unused:UNUSED_PAD src0_sel:DWORD
	v_cvt_f16_f32_e32 v31, v32
	v_cvt_f16_f32_sdwa v32, v33 dst_sel:WORD_1 dst_unused:UNUSED_PAD src0_sel:DWORD
	v_cvt_f16_f32_e32 v33, v34
	v_cvt_f16_f32_sdwa v34, v35 dst_sel:WORD_1 dst_unused:UNUSED_PAD src0_sel:DWORD
	v_cvt_f16_f32_e32 v35, v60
	v_cvt_f16_f32_sdwa v60, v61 dst_sel:WORD_1 dst_unused:UNUSED_PAD src0_sel:DWORD
	v_cvt_f16_f32_e32 v61, v62
	v_cvt_f16_f32_sdwa v62, v63 dst_sel:WORD_1 dst_unused:UNUSED_PAD src0_sel:DWORD
	v_or_b32_e32 v28, v28, v2
	v_or_b32_e32 v29, v30, v29
	v_or_b32_e32 v30, v32, v31
	v_or_b32_e32 v31, v34, v33
	v_or_b32_e32 v32, v60, v35
	v_or_b32_e32 v33, v62, v61
	global_store_dwordx2 v[180:181], v[28:29], off
	global_store_dwordx2 v[182:183], v[30:31], off
	global_store_dwordx2 v[184:185], v[32:33], off
	v_sub_f32_e32 v29, v93, v136
	v_sub_f32_e32 v28, v92, v136
	v_pk_mul_f32 v[28:29], v[136:137], v[28:29] op_sel:[1,0]
	v_pk_mul_f32 v[30:31], v[136:137], v[94:95] op_sel:[1,0]
	v_pk_fma_f32 v[66:67], v[66:67], v[150:151], v[154:155]
	v_pk_fma_f32 v[64:65], v[64:65], v[148:149], v[152:153]
	v_pk_fma_f32 v[30:31], v[30:31], v[150:151], v[154:155]
	v_pk_fma_f32 v[28:29], v[28:29], v[148:149], v[152:153]
	v_cvt_f16_f32_e32 v63, v64
	v_cvt_f16_f32_sdwa v64, v65 dst_sel:WORD_1 dst_unused:UNUSED_PAD src0_sel:DWORD
	v_cvt_f16_f32_e32 v65, v66
	v_cvt_f16_f32_sdwa v66, v67 dst_sel:WORD_1 dst_unused:UNUSED_PAD src0_sel:DWORD
	v_cvt_f16_f32_e32 v28, v28
	v_cvt_f16_f32_sdwa v29, v29 dst_sel:WORD_1 dst_unused:UNUSED_PAD src0_sel:DWORD
	v_cvt_f16_f32_e32 v30, v30
	v_cvt_f16_f32_sdwa v31, v31 dst_sel:WORD_1 dst_unused:UNUSED_PAD src0_sel:DWORD
	v_add_u32_e32 v2, v165, v164
	v_or_b32_e32 v34, v64, v63
	v_or_b32_e32 v35, v66, v65
	v_or_b32_e32 v28, v29, v28
	v_or_b32_e32 v29, v31, v30
	v_lshl_add_u64 v[30:31], v[2:3], 1, s[0:1]
	global_store_dwordx2 v[186:187], v[34:35], off
	global_store_dwordx2 v[30:31], v[28:29], off
	v_sub_f32_e32 v29, v99, v138
	v_sub_f32_e32 v28, v98, v138
	v_sub_f32_e32 v31, v97, v138
	v_sub_f32_e32 v30, v96, v138
	v_pk_mul_f32 v[30:31], v[138:139], v[30:31] op_sel:[1,0]
	v_pk_mul_f32 v[28:29], v[138:139], v[28:29] op_sel:[1,0]
	v_pk_fma_f32 v[30:31], v[148:149], v[30:31], v[152:153]
	v_pk_fma_f32 v[28:29], v[150:151], v[28:29], v[154:155]
	v_cvt_f16_f32_e32 v30, v30
	v_cvt_f16_f32_sdwa v31, v31 dst_sel:WORD_1 dst_unused:UNUSED_PAD src0_sel:DWORD
	v_cvt_f16_f32_e32 v32, v28
	v_cvt_f16_f32_sdwa v29, v29 dst_sel:WORD_1 dst_unused:UNUSED_PAD src0_sel:DWORD
	v_add_u32_e32 v28, 0x24000, v177
	v_add_u32_e32 v2, v165, v28
	v_or_b32_e32 v30, v31, v30
	v_or_b32_e32 v31, v29, v32
	v_lshl_add_u64 v[32:33], v[2:3], 1, s[0:1]
	global_store_dwordx2 v[32:33], v[30:31], off
	s_waitcnt lgkmcnt(0)
	v_sub_f32_e32 v31, v127, v132
	v_sub_f32_e32 v30, v126, v132
	v_sub_f32_e32 v33, v125, v132
	v_sub_f32_e32 v32, v124, v132
	v_pk_mul_f32 v[32:33], v[132:133], v[32:33] op_sel:[1,0]
	v_pk_mul_f32 v[30:31], v[132:133], v[30:31] op_sel:[1,0]
	v_pk_fma_f32 v[32:33], v[148:149], v[32:33], v[152:153]
	v_pk_fma_f32 v[30:31], v[150:151], v[30:31], v[154:155]
	v_cvt_f16_f32_e32 v32, v32
	v_cvt_f16_f32_sdwa v33, v33 dst_sel:WORD_1 dst_unused:UNUSED_PAD src0_sel:DWORD
	v_cvt_f16_f32_e32 v34, v30
	v_cvt_f16_f32_sdwa v31, v31 dst_sel:WORD_1 dst_unused:UNUSED_PAD src0_sel:DWORD
	v_add_u32_e32 v29, 0x28000, v177
	v_add_u32_e32 v2, v165, v29
	v_or_b32_e32 v30, v33, v32
	v_or_b32_e32 v31, v31, v34
	v_lshl_add_u64 v[32:33], v[2:3], 1, s[0:1]
	global_store_dwordx2 v[32:33], v[30:31], off
	v_sub_f32_e32 v31, v131, v134
	v_sub_f32_e32 v30, v130, v134
	v_sub_f32_e32 v33, v129, v134
	v_sub_f32_e32 v32, v128, v134
	v_pk_mul_f32 v[32:33], v[134:135], v[32:33] op_sel:[1,0]
	v_pk_mul_f32 v[30:31], v[134:135], v[30:31] op_sel:[1,0]
	v_pk_fma_f32 v[32:33], v[148:149], v[32:33], v[152:153]
	v_pk_fma_f32 v[30:31], v[150:151], v[30:31], v[154:155]
	v_cvt_f16_f32_e32 v32, v32
	v_cvt_f16_f32_sdwa v33, v33 dst_sel:WORD_1 dst_unused:UNUSED_PAD src0_sel:DWORD
	v_cvt_f16_f32_e32 v34, v30
	v_cvt_f16_f32_sdwa v31, v31 dst_sel:WORD_1 dst_unused:UNUSED_PAD src0_sel:DWORD
	v_add_u32_e32 v30, 0x2c000, v177
	v_add_u32_e32 v2, v165, v30
	v_or_b32_e32 v32, v33, v32
	v_or_b32_e32 v33, v31, v34
	v_lshl_add_u64 v[34:35], v[2:3], 1, s[0:1]
	global_store_dwordx2 v[34:35], v[32:33], off
	s_nop 1
	v_mov_b32_e32 v32, v200
	v_mov_b32_e32 v33, v201
	v_mov_b32_e32 v34, v202
	v_mov_b32_e32 v35, v203
	s_nop 0
	s_nop 1
	v_mov_b32_e32 v60, v204
	v_mov_b32_e32 v61, v205
	v_mov_b32_e32 v62, v206
	v_mov_b32_e32 v63, v207
	v_or_b32_e32 v31, 16, v165
	v_add_u32_e32 v2, v31, v177
	v_pk_fma_f32 v[22:23], v[22:23], v[34:35], v[62:63]
	v_pk_fma_f32 v[20:21], v[20:21], v[32:33], v[60:61]
	v_cvt_f16_f32_e32 v22, v22
	v_cvt_f16_f32_e32 v20, v20
	v_cvt_f16_f32_sdwa v21, v21 dst_sel:WORD_1 dst_unused:UNUSED_PAD src0_sel:DWORD
	v_cvt_f16_f32_sdwa v23, v23 dst_sel:WORD_1 dst_unused:UNUSED_PAD src0_sel:DWORD
	v_pk_fma_f32 v[26:27], v[26:27], v[34:35], v[62:63]
	v_pk_fma_f32 v[24:25], v[24:25], v[32:33], v[60:61]
	v_cvt_f16_f32_e32 v26, v26
	v_cvt_f16_f32_e32 v24, v24
	v_cvt_f16_f32_sdwa v25, v25 dst_sel:WORD_1 dst_unused:UNUSED_PAD src0_sel:DWORD
	v_cvt_f16_f32_sdwa v27, v27 dst_sel:WORD_1 dst_unused:UNUSED_PAD src0_sel:DWORD
	v_or_b32_e32 v20, v21, v20
	v_or_b32_e32 v21, v23, v22
	v_lshl_add_u64 v[22:23], v[2:3], 1, s[0:1]
	global_store_dwordx2 v[22:23], v[20:21], off
	v_or_b32_e32 v20, v25, v24
	v_or_b32_e32 v21, v27, v26
	v_sub_f32_e32 v25, v55, v140
	v_sub_f32_e32 v24, v54, v140
	v_sub_f32_e32 v27, v53, v140
	v_sub_f32_e32 v26, v52, v140
	v_pk_mul_f32 v[26:27], v[140:141], v[26:27] op_sel:[1,0]
	v_pk_mul_f32 v[24:25], v[140:141], v[24:25] op_sel:[1,0]
	v_pk_fma_f32 v[26:27], v[26:27], v[32:33], v[60:61]
	v_pk_fma_f32 v[24:25], v[24:25], v[34:35], v[62:63]
	v_cvt_f16_f32_e32 v26, v26
	v_cvt_f16_f32_sdwa v27, v27 dst_sel:WORD_1 dst_unused:UNUSED_PAD src0_sel:DWORD
	v_cvt_f16_f32_e32 v24, v24
	v_cvt_f16_f32_sdwa v25, v25 dst_sel:WORD_1 dst_unused:UNUSED_PAD src0_sel:DWORD
	v_add_u32_e32 v2, v31, v179
	v_lshl_add_u64 v[22:23], v[2:3], 1, s[0:1]
	global_store_dwordx2 v[22:23], v[20:21], off
	v_or_b32_e32 v20, v27, v26
	v_or_b32_e32 v21, v25, v24
	v_sub_f32_e32 v25, v59, v142
	v_sub_f32_e32 v24, v58, v142
	v_sub_f32_e32 v27, v57, v142
	v_sub_f32_e32 v26, v56, v142
	v_pk_mul_f32 v[26:27], v[142:143], v[26:27] op_sel:[1,0]
	v_pk_mul_f32 v[24:25], v[142:143], v[24:25] op_sel:[1,0]
	v_pk_fma_f32 v[26:27], v[26:27], v[32:33], v[60:61]
	v_pk_fma_f32 v[24:25], v[24:25], v[34:35], v[62:63]
	v_cvt_f16_f32_e32 v26, v26
	v_cvt_f16_f32_sdwa v27, v27 dst_sel:WORD_1 dst_unused:UNUSED_PAD src0_sel:DWORD
	v_cvt_f16_f32_e32 v24, v24
	v_cvt_f16_f32_sdwa v25, v25 dst_sel:WORD_1 dst_unused:UNUSED_PAD src0_sel:DWORD
	v_add_u32_e32 v2, v31, v178
	v_lshl_add_u64 v[22:23], v[2:3], 1, s[0:1]
	global_store_dwordx2 v[22:23], v[20:21], off
	v_or_b32_e32 v20, v27, v26
	v_or_b32_e32 v21, v25, v24
	v_sub_f32_e32 v25, v87, v136
	v_sub_f32_e32 v24, v86, v136
	v_sub_f32_e32 v27, v85, v136
	v_sub_f32_e32 v26, v84, v136
	v_pk_mul_f32 v[26:27], v[136:137], v[26:27] op_sel:[1,0]
	v_pk_mul_f32 v[24:25], v[136:137], v[24:25] op_sel:[1,0]
	v_pk_fma_f32 v[26:27], v[26:27], v[32:33], v[60:61]
	v_pk_fma_f32 v[24:25], v[24:25], v[34:35], v[62:63]
	v_cvt_f16_f32_e32 v26, v26
	v_cvt_f16_f32_sdwa v27, v27 dst_sel:WORD_1 dst_unused:UNUSED_PAD src0_sel:DWORD
	v_cvt_f16_f32_e32 v24, v24
	v_cvt_f16_f32_sdwa v25, v25 dst_sel:WORD_1 dst_unused:UNUSED_PAD src0_sel:DWORD
	v_add_u32_e32 v2, v31, v176
	v_lshl_add_u64 v[22:23], v[2:3], 1, s[0:1]
	global_store_dwordx2 v[22:23], v[20:21], off
	v_or_b32_e32 v20, v27, v26
	v_or_b32_e32 v21, v25, v24
	v_sub_f32_e32 v25, v91, v138
	v_sub_f32_e32 v24, v90, v138
	v_sub_f32_e32 v27, v89, v138
	v_sub_f32_e32 v26, v88, v138
	v_pk_mul_f32 v[26:27], v[138:139], v[26:27] op_sel:[1,0]
	v_pk_mul_f32 v[24:25], v[138:139], v[24:25] op_sel:[1,0]
	v_pk_fma_f32 v[26:27], v[26:27], v[32:33], v[60:61]
	v_pk_fma_f32 v[24:25], v[24:25], v[34:35], v[62:63]
	v_cvt_f16_f32_e32 v26, v26
	v_cvt_f16_f32_sdwa v27, v27 dst_sel:WORD_1 dst_unused:UNUSED_PAD src0_sel:DWORD
	v_cvt_f16_f32_e32 v24, v24
	v_cvt_f16_f32_sdwa v25, v25 dst_sel:WORD_1 dst_unused:UNUSED_PAD src0_sel:DWORD
	v_add_u32_e32 v2, v31, v164
	v_lshl_add_u64 v[22:23], v[2:3], 1, s[0:1]
	global_store_dwordx2 v[22:23], v[20:21], off
	v_or_b32_e32 v20, v27, v26
	v_or_b32_e32 v21, v25, v24
	v_sub_f32_e32 v25, v119, v132
	v_sub_f32_e32 v24, v118, v132
	v_sub_f32_e32 v27, v117, v132
	v_sub_f32_e32 v26, v116, v132
	v_pk_mul_f32 v[26:27], v[132:133], v[26:27] op_sel:[1,0]
	v_pk_mul_f32 v[24:25], v[132:133], v[24:25] op_sel:[1,0]
	v_pk_fma_f32 v[26:27], v[26:27], v[32:33], v[60:61]
	v_pk_fma_f32 v[24:25], v[24:25], v[34:35], v[62:63]
	v_cvt_f16_f32_e32 v26, v26
	v_cvt_f16_f32_sdwa v27, v27 dst_sel:WORD_1 dst_unused:UNUSED_PAD src0_sel:DWORD
	v_cvt_f16_f32_e32 v24, v24
	v_cvt_f16_f32_sdwa v25, v25 dst_sel:WORD_1 dst_unused:UNUSED_PAD src0_sel:DWORD
	v_add_u32_e32 v2, v31, v28
	v_lshl_add_u64 v[22:23], v[2:3], 1, s[0:1]
	global_store_dwordx2 v[22:23], v[20:21], off
	v_or_b32_e32 v20, v27, v26
	v_or_b32_e32 v21, v25, v24
	v_sub_f32_e32 v25, v123, v134
	v_sub_f32_e32 v24, v122, v134
	v_sub_f32_e32 v27, v121, v134
	v_sub_f32_e32 v26, v120, v134
	v_pk_mul_f32 v[26:27], v[134:135], v[26:27] op_sel:[1,0]
	v_pk_mul_f32 v[24:25], v[134:135], v[24:25] op_sel:[1,0]
	v_pk_fma_f32 v[26:27], v[26:27], v[32:33], v[60:61]
	v_pk_fma_f32 v[24:25], v[24:25], v[34:35], v[62:63]
	v_cvt_f16_f32_e32 v26, v26
	v_cvt_f16_f32_sdwa v27, v27 dst_sel:WORD_1 dst_unused:UNUSED_PAD src0_sel:DWORD
	v_cvt_f16_f32_e32 v24, v24
	v_cvt_f16_f32_sdwa v25, v25 dst_sel:WORD_1 dst_unused:UNUSED_PAD src0_sel:DWORD
	v_add_u32_e32 v2, v31, v29
	v_lshl_add_u64 v[22:23], v[2:3], 1, s[0:1]
	v_add_u32_e32 v2, v31, v30
	global_store_dwordx2 v[22:23], v[20:21], off
	v_or_b32_e32 v20, v27, v26
	v_or_b32_e32 v21, v25, v24
	v_lshl_add_u64 v[22:23], v[2:3], 1, s[0:1]
	global_store_dwordx2 v[22:23], v[20:21], off
	s_nop 1
	v_mov_b32_e32 v20, v208
	v_mov_b32_e32 v21, v209
	v_mov_b32_e32 v22, v210
	v_mov_b32_e32 v23, v211
	s_nop 0
	s_nop 1
	v_mov_b32_e32 v24, v212
	v_mov_b32_e32 v25, v213
	v_mov_b32_e32 v26, v214
	v_mov_b32_e32 v27, v215
	v_or_b32_e32 v31, 0x80, v165
	v_add_u32_e32 v2, v31, v177
	v_pk_fma_f32 v[14:15], v[14:15], v[22:23], v[26:27]
	v_pk_fma_f32 v[12:13], v[12:13], v[20:21], v[24:25]
	v_cvt_f16_f32_e32 v14, v14
	v_cvt_f16_f32_e32 v12, v12
	v_cvt_f16_f32_sdwa v13, v13 dst_sel:WORD_1 dst_unused:UNUSED_PAD src0_sel:DWORD
	v_cvt_f16_f32_sdwa v15, v15 dst_sel:WORD_1 dst_unused:UNUSED_PAD src0_sel:DWORD
	v_pk_fma_f32 v[18:19], v[18:19], v[22:23], v[26:27]
	v_pk_fma_f32 v[16:17], v[16:17], v[20:21], v[24:25]
	v_cvt_f16_f32_e32 v18, v18
	v_cvt_f16_f32_e32 v16, v16
	v_cvt_f16_f32_sdwa v17, v17 dst_sel:WORD_1 dst_unused:UNUSED_PAD src0_sel:DWORD
	v_cvt_f16_f32_sdwa v19, v19 dst_sel:WORD_1 dst_unused:UNUSED_PAD src0_sel:DWORD
	v_or_b32_e32 v12, v13, v12
	v_or_b32_e32 v13, v15, v14
	v_lshl_add_u64 v[14:15], v[2:3], 1, s[0:1]
	global_store_dwordx2 v[14:15], v[12:13], off
	v_or_b32_e32 v12, v17, v16
	v_or_b32_e32 v13, v19, v18
	v_sub_f32_e32 v17, v47, v140
	v_sub_f32_e32 v16, v46, v140
	v_sub_f32_e32 v19, v45, v140
	v_sub_f32_e32 v18, v44, v140
	v_pk_mul_f32 v[18:19], v[140:141], v[18:19] op_sel:[1,0]
	v_pk_mul_f32 v[16:17], v[140:141], v[16:17] op_sel:[1,0]
	v_pk_fma_f32 v[18:19], v[18:19], v[20:21], v[24:25]
	v_pk_fma_f32 v[16:17], v[16:17], v[22:23], v[26:27]
	v_cvt_f16_f32_e32 v18, v18
	v_cvt_f16_f32_sdwa v19, v19 dst_sel:WORD_1 dst_unused:UNUSED_PAD src0_sel:DWORD
	v_cvt_f16_f32_e32 v16, v16
	v_cvt_f16_f32_sdwa v17, v17 dst_sel:WORD_1 dst_unused:UNUSED_PAD src0_sel:DWORD
	v_add_u32_e32 v2, v31, v179
	v_lshl_add_u64 v[14:15], v[2:3], 1, s[0:1]
	global_store_dwordx2 v[14:15], v[12:13], off
	v_or_b32_e32 v12, v19, v18
	v_or_b32_e32 v13, v17, v16
	v_sub_f32_e32 v17, v51, v142
	v_sub_f32_e32 v16, v50, v142
	v_sub_f32_e32 v19, v49, v142
	v_sub_f32_e32 v18, v48, v142
	v_pk_mul_f32 v[18:19], v[142:143], v[18:19] op_sel:[1,0]
	v_pk_mul_f32 v[16:17], v[142:143], v[16:17] op_sel:[1,0]
	v_pk_fma_f32 v[18:19], v[18:19], v[20:21], v[24:25]
	v_pk_fma_f32 v[16:17], v[16:17], v[22:23], v[26:27]
	v_cvt_f16_f32_e32 v18, v18
	v_cvt_f16_f32_sdwa v19, v19 dst_sel:WORD_1 dst_unused:UNUSED_PAD src0_sel:DWORD
	v_cvt_f16_f32_e32 v16, v16
	v_cvt_f16_f32_sdwa v17, v17 dst_sel:WORD_1 dst_unused:UNUSED_PAD src0_sel:DWORD
	v_add_u32_e32 v2, v31, v178
	v_lshl_add_u64 v[14:15], v[2:3], 1, s[0:1]
	global_store_dwordx2 v[14:15], v[12:13], off
	v_or_b32_e32 v12, v19, v18
	v_or_b32_e32 v13, v17, v16
	v_sub_f32_e32 v17, v79, v136
	v_sub_f32_e32 v16, v78, v136
	v_sub_f32_e32 v19, v77, v136
	v_sub_f32_e32 v18, v76, v136
	v_pk_mul_f32 v[18:19], v[136:137], v[18:19] op_sel:[1,0]
	v_pk_mul_f32 v[16:17], v[136:137], v[16:17] op_sel:[1,0]
	v_pk_fma_f32 v[18:19], v[18:19], v[20:21], v[24:25]
	v_pk_fma_f32 v[16:17], v[16:17], v[22:23], v[26:27]
	v_cvt_f16_f32_e32 v18, v18
	v_cvt_f16_f32_sdwa v19, v19 dst_sel:WORD_1 dst_unused:UNUSED_PAD src0_sel:DWORD
	v_cvt_f16_f32_e32 v16, v16
	v_cvt_f16_f32_sdwa v17, v17 dst_sel:WORD_1 dst_unused:UNUSED_PAD src0_sel:DWORD
	v_add_u32_e32 v2, v31, v176
	v_lshl_add_u64 v[14:15], v[2:3], 1, s[0:1]
	global_store_dwordx2 v[14:15], v[12:13], off
	v_or_b32_e32 v12, v19, v18
	v_or_b32_e32 v13, v17, v16
	v_sub_f32_e32 v17, v83, v138
	v_sub_f32_e32 v16, v82, v138
	v_sub_f32_e32 v19, v81, v138
	v_sub_f32_e32 v18, v80, v138
	v_pk_mul_f32 v[18:19], v[138:139], v[18:19] op_sel:[1,0]
	v_pk_mul_f32 v[16:17], v[138:139], v[16:17] op_sel:[1,0]
	v_pk_fma_f32 v[18:19], v[18:19], v[20:21], v[24:25]
	v_pk_fma_f32 v[16:17], v[16:17], v[22:23], v[26:27]
	v_cvt_f16_f32_e32 v18, v18
	v_cvt_f16_f32_sdwa v19, v19 dst_sel:WORD_1 dst_unused:UNUSED_PAD src0_sel:DWORD
	v_cvt_f16_f32_e32 v16, v16
	v_cvt_f16_f32_sdwa v17, v17 dst_sel:WORD_1 dst_unused:UNUSED_PAD src0_sel:DWORD
	v_add_u32_e32 v2, v31, v164
	v_lshl_add_u64 v[14:15], v[2:3], 1, s[0:1]
	global_store_dwordx2 v[14:15], v[12:13], off
	v_or_b32_e32 v12, v19, v18
	v_or_b32_e32 v13, v17, v16
	v_sub_f32_e32 v17, v111, v132
	v_sub_f32_e32 v16, v110, v132
	v_sub_f32_e32 v19, v109, v132
	v_sub_f32_e32 v18, v108, v132
	v_pk_mul_f32 v[18:19], v[132:133], v[18:19] op_sel:[1,0]
	v_pk_mul_f32 v[16:17], v[132:133], v[16:17] op_sel:[1,0]
	v_pk_fma_f32 v[18:19], v[18:19], v[20:21], v[24:25]
	v_pk_fma_f32 v[16:17], v[16:17], v[22:23], v[26:27]
	v_cvt_f16_f32_e32 v18, v18
	v_cvt_f16_f32_sdwa v19, v19 dst_sel:WORD_1 dst_unused:UNUSED_PAD src0_sel:DWORD
	v_cvt_f16_f32_e32 v16, v16
	v_cvt_f16_f32_sdwa v17, v17 dst_sel:WORD_1 dst_unused:UNUSED_PAD src0_sel:DWORD
	v_add_u32_e32 v2, v31, v28
	v_lshl_add_u64 v[14:15], v[2:3], 1, s[0:1]
	global_store_dwordx2 v[14:15], v[12:13], off
	v_or_b32_e32 v12, v19, v18
	v_or_b32_e32 v13, v17, v16
	v_sub_f32_e32 v17, v115, v134
	v_sub_f32_e32 v16, v114, v134
	v_sub_f32_e32 v19, v113, v134
	v_sub_f32_e32 v18, v112, v134
	v_pk_mul_f32 v[18:19], v[134:135], v[18:19] op_sel:[1,0]
	v_pk_mul_f32 v[16:17], v[134:135], v[16:17] op_sel:[1,0]
	v_pk_fma_f32 v[18:19], v[18:19], v[20:21], v[24:25]
	v_pk_fma_f32 v[16:17], v[16:17], v[22:23], v[26:27]
	v_cvt_f16_f32_e32 v18, v18
	v_cvt_f16_f32_sdwa v19, v19 dst_sel:WORD_1 dst_unused:UNUSED_PAD src0_sel:DWORD
	v_cvt_f16_f32_e32 v16, v16
	v_cvt_f16_f32_sdwa v17, v17 dst_sel:WORD_1 dst_unused:UNUSED_PAD src0_sel:DWORD
	v_add_u32_e32 v2, v31, v29
	v_lshl_add_u64 v[14:15], v[2:3], 1, s[0:1]
	v_add_u32_e32 v2, v31, v30
	global_store_dwordx2 v[14:15], v[12:13], off
	v_or_b32_e32 v12, v19, v18
	v_or_b32_e32 v13, v17, v16
	v_lshl_add_u64 v[14:15], v[2:3], 1, s[0:1]
	global_store_dwordx2 v[14:15], v[12:13], off
	s_nop 1
	v_mov_b32_e32 v12, v216
	v_mov_b32_e32 v13, v217
	v_mov_b32_e32 v14, v218
	v_mov_b32_e32 v15, v219
	s_nop 0
	s_nop 1
	v_mov_b32_e32 v16, v220
	v_mov_b32_e32 v17, v221
	v_mov_b32_e32 v18, v222
	v_mov_b32_e32 v19, v223
	v_sub_f32_e32 v1, v7, v144
	v_sub_f32_e32 v0, v6, v144
	v_pk_mul_f32 v[0:1], v[144:145], v[0:1] op_sel:[1,0]
	v_sub_f32_e32 v7, v11, v146
	v_or_b32_e32 v20, 0x90, v165
	v_add_u32_e32 v2, v20, v177
	v_pk_fma_f32 v[0:1], v[0:1], v[14:15], v[18:19]
	s_nop 0
	v_cvt_f16_f32_e32 v6, v0
	v_cvt_f16_f32_sdwa v1, v1 dst_sel:WORD_1 dst_unused:UNUSED_PAD src0_sel:DWORD
	v_pk_fma_f32 v[4:5], v[4:5], v[12:13], v[16:17]
	v_pk_fma_f32 v[8:9], v[8:9], v[12:13], v[16:17]
	v_cvt_f16_f32_e32 v4, v4
	v_or_b32_e32 v1, v1, v6
	v_sub_f32_e32 v6, v10, v146
	v_pk_mul_f32 v[6:7], v[146:147], v[6:7] op_sel:[1,0]
	v_cvt_f16_f32_sdwa v5, v5 dst_sel:WORD_1 dst_unused:UNUSED_PAD src0_sel:DWORD
	v_pk_fma_f32 v[6:7], v[6:7], v[14:15], v[18:19]
	v_cvt_f16_f32_e32 v8, v8
	v_cvt_f16_f32_sdwa v9, v9 dst_sel:WORD_1 dst_unused:UNUSED_PAD src0_sel:DWORD
	v_cvt_f16_f32_e32 v6, v6
	v_cvt_f16_f32_sdwa v7, v7 dst_sel:WORD_1 dst_unused:UNUSED_PAD src0_sel:DWORD
	v_or_b32_e32 v0, v5, v4
	v_lshl_add_u64 v[4:5], v[2:3], 1, s[0:1]
	global_store_dwordx2 v[4:5], v[0:1], off
	v_or_b32_e32 v0, v9, v8
	v_or_b32_e32 v1, v7, v6
	v_sub_f32_e32 v7, v39, v140
	v_sub_f32_e32 v6, v38, v140
	v_sub_f32_e32 v9, v37, v140
	v_sub_f32_e32 v8, v36, v140
	v_pk_mul_f32 v[8:9], v[140:141], v[8:9] op_sel:[1,0]
	v_pk_mul_f32 v[6:7], v[140:141], v[6:7] op_sel:[1,0]
	v_pk_fma_f32 v[8:9], v[8:9], v[12:13], v[16:17]
	v_pk_fma_f32 v[6:7], v[6:7], v[14:15], v[18:19]
	v_cvt_f16_f32_e32 v8, v8
	v_cvt_f16_f32_sdwa v9, v9 dst_sel:WORD_1 dst_unused:UNUSED_PAD src0_sel:DWORD
	v_cvt_f16_f32_e32 v6, v6
	v_cvt_f16_f32_sdwa v7, v7 dst_sel:WORD_1 dst_unused:UNUSED_PAD src0_sel:DWORD
	v_add_u32_e32 v2, v20, v179
	v_lshl_add_u64 v[4:5], v[2:3], 1, s[0:1]
	global_store_dwordx2 v[4:5], v[0:1], off
	v_or_b32_e32 v0, v9, v8
	v_or_b32_e32 v1, v7, v6
	v_sub_f32_e32 v7, v43, v142
	v_sub_f32_e32 v6, v42, v142
	v_sub_f32_e32 v9, v41, v142
	v_sub_f32_e32 v8, v40, v142
	v_pk_mul_f32 v[8:9], v[142:143], v[8:9] op_sel:[1,0]
	v_pk_mul_f32 v[6:7], v[142:143], v[6:7] op_sel:[1,0]
	v_pk_fma_f32 v[8:9], v[8:9], v[12:13], v[16:17]
	v_pk_fma_f32 v[6:7], v[6:7], v[14:15], v[18:19]
	v_cvt_f16_f32_e32 v8, v8
	v_cvt_f16_f32_sdwa v9, v9 dst_sel:WORD_1 dst_unused:UNUSED_PAD src0_sel:DWORD
	v_cvt_f16_f32_e32 v6, v6
	v_cvt_f16_f32_sdwa v7, v7 dst_sel:WORD_1 dst_unused:UNUSED_PAD src0_sel:DWORD
	v_add_u32_e32 v2, v20, v178
	v_lshl_add_u64 v[4:5], v[2:3], 1, s[0:1]
	global_store_dwordx2 v[4:5], v[0:1], off
	v_or_b32_e32 v0, v9, v8
	v_or_b32_e32 v1, v7, v6
	v_sub_f32_e32 v7, v71, v136
	v_sub_f32_e32 v6, v70, v136
	v_sub_f32_e32 v9, v69, v136
	v_sub_f32_e32 v8, v68, v136
	v_pk_mul_f32 v[8:9], v[136:137], v[8:9] op_sel:[1,0]
	v_pk_mul_f32 v[6:7], v[136:137], v[6:7] op_sel:[1,0]
	v_pk_fma_f32 v[8:9], v[8:9], v[12:13], v[16:17]
	v_pk_fma_f32 v[6:7], v[6:7], v[14:15], v[18:19]
	v_cvt_f16_f32_e32 v8, v8
	v_cvt_f16_f32_sdwa v9, v9 dst_sel:WORD_1 dst_unused:UNUSED_PAD src0_sel:DWORD
	v_cvt_f16_f32_e32 v6, v6
	v_cvt_f16_f32_sdwa v7, v7 dst_sel:WORD_1 dst_unused:UNUSED_PAD src0_sel:DWORD
	v_add_u32_e32 v2, v20, v176
	v_lshl_add_u64 v[4:5], v[2:3], 1, s[0:1]
	global_store_dwordx2 v[4:5], v[0:1], off
	v_or_b32_e32 v0, v9, v8
	v_or_b32_e32 v1, v7, v6
	v_sub_f32_e32 v7, v75, v138
	v_sub_f32_e32 v6, v74, v138
	v_sub_f32_e32 v9, v73, v138
	v_sub_f32_e32 v8, v72, v138
	v_pk_mul_f32 v[8:9], v[138:139], v[8:9] op_sel:[1,0]
	v_pk_mul_f32 v[6:7], v[138:139], v[6:7] op_sel:[1,0]
	v_pk_fma_f32 v[8:9], v[8:9], v[12:13], v[16:17]
	v_pk_fma_f32 v[6:7], v[6:7], v[14:15], v[18:19]
	v_cvt_f16_f32_e32 v8, v8
	v_cvt_f16_f32_sdwa v9, v9 dst_sel:WORD_1 dst_unused:UNUSED_PAD src0_sel:DWORD
	v_cvt_f16_f32_e32 v6, v6
	v_cvt_f16_f32_sdwa v7, v7 dst_sel:WORD_1 dst_unused:UNUSED_PAD src0_sel:DWORD
	v_add_u32_e32 v2, v20, v164
	v_lshl_add_u64 v[4:5], v[2:3], 1, s[0:1]
	global_store_dwordx2 v[4:5], v[0:1], off
	v_or_b32_e32 v0, v9, v8
	v_or_b32_e32 v1, v7, v6
	v_sub_f32_e32 v7, v103, v132
	v_sub_f32_e32 v6, v102, v132
	v_sub_f32_e32 v9, v101, v132
	v_sub_f32_e32 v8, v100, v132
	v_pk_mul_f32 v[8:9], v[132:133], v[8:9] op_sel:[1,0]
	v_pk_mul_f32 v[6:7], v[132:133], v[6:7] op_sel:[1,0]
	v_pk_fma_f32 v[8:9], v[8:9], v[12:13], v[16:17]
	v_pk_fma_f32 v[6:7], v[6:7], v[14:15], v[18:19]
	v_cvt_f16_f32_e32 v8, v8
	v_cvt_f16_f32_sdwa v9, v9 dst_sel:WORD_1 dst_unused:UNUSED_PAD src0_sel:DWORD
	v_cvt_f16_f32_e32 v6, v6
	v_cvt_f16_f32_sdwa v7, v7 dst_sel:WORD_1 dst_unused:UNUSED_PAD src0_sel:DWORD
	v_add_u32_e32 v2, v20, v28
	v_lshl_add_u64 v[4:5], v[2:3], 1, s[0:1]
	global_store_dwordx2 v[4:5], v[0:1], off
	v_or_b32_e32 v0, v9, v8
	v_or_b32_e32 v1, v7, v6
	v_sub_f32_e32 v7, v107, v134
	v_sub_f32_e32 v6, v106, v134
	v_sub_f32_e32 v9, v105, v134
	v_sub_f32_e32 v8, v104, v134
	v_pk_mul_f32 v[8:9], v[134:135], v[8:9] op_sel:[1,0]
	v_pk_mul_f32 v[6:7], v[134:135], v[6:7] op_sel:[1,0]
	v_pk_fma_f32 v[8:9], v[8:9], v[12:13], v[16:17]
	v_pk_fma_f32 v[6:7], v[6:7], v[14:15], v[18:19]
	v_cvt_f16_f32_e32 v8, v8
	v_cvt_f16_f32_sdwa v9, v9 dst_sel:WORD_1 dst_unused:UNUSED_PAD src0_sel:DWORD
	v_cvt_f16_f32_e32 v6, v6
	v_cvt_f16_f32_sdwa v7, v7 dst_sel:WORD_1 dst_unused:UNUSED_PAD src0_sel:DWORD
	v_add_u32_e32 v2, v20, v29
	v_lshl_add_u64 v[4:5], v[2:3], 1, s[0:1]
	v_add_u32_e32 v2, v20, v30
	global_store_dwordx2 v[4:5], v[0:1], off
	v_or_b32_e32 v0, v9, v8
	v_or_b32_e32 v1, v7, v6
	v_lshl_add_u64 v[4:5], v[2:3], 1, s[0:1]
	global_store_dwordx2 v[4:5], v[0:1], off

.LBB0_554:
	s_waitcnt vmcnt(0) lgkmcnt(0)
	s_barrier
	s_and_saveexec_b64 s[6:7], s[4:5]
	s_cbranch_execz .LBB0_556
	v_readlane_b32 s0, v252, 61
	v_lshlrev_b64 v[0:1], 5, v[0:1]
	v_readlane_b32 s1, v252, 62
	s_nop 1
	v_lshl_add_u64 v[0:1], s[0:1], 0, v[0:1]
	global_load_dwordx2 v[132:133], v[0:1], off sc1
	global_load_dwordx2 v[134:135], v[0:1], off offset:8 sc1
	global_load_dwordx2 v[234:235], v[0:1], off offset:16 sc1
	global_load_dwordx2 v[236:237], v[0:1], off offset:24 sc1
	s_mov_b32 s0, 0xf800000
	s_waitcnt vmcnt(3)
	v_add_f32_e32 v136, 0, v132
	s_waitcnt vmcnt(2)
	v_add_f32_e32 v138, v136, v134
	s_waitcnt vmcnt(1)
	v_mov_b32_e32 v136, v234
	v_mov_b32_e32 v137, v235
	v_add_f32_e32 v138, v138, v136
	s_waitcnt vmcnt(0)
	v_mov_b32_e32 v0, v236
	v_mov_b32_e32 v1, v237
	v_add_f32_e32 v139, v138, v0
	v_fmamk_f32 v132, v139, 0xbe800000, v132
	v_mul_f32_e32 v140, 0x43800000, v132
	v_fmac_f32_e32 v133, v132, v140
	v_add_f32_e32 v132, 0, v133
	v_fmamk_f32 v133, v139, 0xbe800000, v134
	v_mul_f32_e32 v134, 0x43800000, v133
	v_fmac_f32_e32 v135, v133, v134
	v_fmamk_f32 v133, v139, 0xbe800000, v136
	v_mul_f32_e32 v134, 0x43800000, v133
	v_fmamk_f32 v0, v139, 0xbe800000, v0
	v_add_f32_e32 v132, v135, v132
	v_fmac_f32_e32 v137, v133, v134
	v_mul_f32_e32 v133, 0x43800000, v0
	v_add_f32_e32 v132, v137, v132
	v_fmac_f32_e32 v1, v0, v133
	v_add_f32_e32 v0, v1, v132
	v_fmamk_f32 v0, v0, 0x3a800000, v173
	v_cmp_gt_f32_e32 vcc, s0, v0
	v_mul_f32_e32 v1, 0x4f800000, v0
	v_mul_f32_e32 v138, 0x3e800000, v139
	v_cndmask_b32_e32 v0, v0, v1, vcc
	v_sqrt_f32_e32 v1, v0
	s_nop 0
	v_add_u32_e32 v132, -1, v1
	v_fma_f32 v133, -v132, v1, v0
	v_cmp_ge_f32_e64 s[0:1], 0, v133
	v_add_u32_e32 v133, 1, v1
	s_nop 0
	v_cndmask_b32_e64 v132, v1, v132, s[0:1]
	v_fma_f32 v1, -v133, v1, v0
	v_cmp_lt_f32_e64 s[0:1], 0, v1
	s_nop 1
	v_cndmask_b32_e64 v1, v132, v133, s[0:1]
	v_mul_f32_e32 v132, 0x37800000, v1
	v_cndmask_b32_e32 v1, v1, v132, vcc
	v_cmp_class_f32_e32 vcc, v0, v174
	s_nop 1
	v_cndmask_b32_e32 v0, v1, v0, vcc
	v_div_scale_f32 v1, s[0:1], v0, v0, 1.0
	v_rcp_f32_e32 v132, v1
	s_nop 0
	v_fma_f32 v133, -v1, v132, 1.0
	v_fmac_f32_e32 v132, v133, v132
	v_div_scale_f32 v133, vcc, 1.0, v0, 1.0
	v_mul_f32_e32 v134, v133, v132
	v_fma_f32 v135, -v1, v134, v133
	v_fmac_f32_e32 v134, v135, v132
	v_fma_f32 v1, -v1, v134, v133
	v_div_fmas_f32 v1, v1, v132, v134
	v_div_fixup_f32 v139, v1, v0, 1.0
	v_lshl_add_u32 v0, v2, 3, 0
	ds_write_b64 v0, v[138:139] offset:8192

.LBB0_1185:
	s_waitcnt vmcnt(0) lgkmcnt(0)
	s_barrier
	s_and_saveexec_b64 s[6:7], s[4:5]
	s_cbranch_execz .LBB0_1187
	v_readlane_b32 s2, v252, 61
	v_lshlrev_b64 v[0:1], 5, v[0:1]
	v_readlane_b32 s3, v252, 62
	s_nop 1
	v_lshl_add_u64 v[0:1], s[2:3], 0, v[0:1]
	global_load_dwordx2 v[132:133], v[0:1], off sc1
	global_load_dwordx2 v[134:135], v[0:1], off offset:8 sc1
	global_load_dwordx2 v[248:249], v[0:1], off offset:16 sc1
	global_load_dwordx2 v[250:251], v[0:1], off offset:24 sc1
	s_mov_b32 s2, 0xf800000
	s_waitcnt vmcnt(3)
	v_add_f32_e32 v136, 0, v132
	s_waitcnt vmcnt(2)
	v_add_f32_e32 v138, v136, v134
	s_waitcnt vmcnt(1)
	v_mov_b32_e32 v136, v248
	v_mov_b32_e32 v137, v249
	v_add_f32_e32 v138, v138, v136
	s_waitcnt vmcnt(0)
	v_mov_b32_e32 v0, v250
	v_mov_b32_e32 v1, v251
	v_add_f32_e32 v139, v138, v0
	v_fmamk_f32 v132, v139, 0xbe800000, v132
	v_mul_f32_e32 v141, 0x43800000, v132
	v_fmac_f32_e32 v133, v132, v141
	v_add_f32_e32 v132, 0, v133
	v_fmamk_f32 v133, v139, 0xbe800000, v134
	v_mul_f32_e32 v134, 0x43800000, v133
	v_fmac_f32_e32 v135, v133, v134
	v_fmamk_f32 v133, v139, 0xbe800000, v136
	v_mul_f32_e32 v134, 0x43800000, v133
	v_fmamk_f32 v0, v139, 0xbe800000, v0
	v_add_f32_e32 v132, v135, v132
	v_fmac_f32_e32 v137, v133, v134
	v_mul_f32_e32 v133, 0x43800000, v0
	v_add_f32_e32 v132, v137, v132
	v_fmac_f32_e32 v1, v0, v133
	v_add_f32_e32 v0, v1, v132
	v_mov_b32_e32 v1, 0x3727c5ac
	v_fmamk_f32 v0, v0, 0x3a800000, v1
	v_cmp_gt_f32_e32 vcc, s2, v0
	v_mul_f32_e32 v1, 0x4f800000, v0
	v_mul_f32_e32 v138, 0x3e800000, v139
	v_cndmask_b32_e32 v0, v0, v1, vcc
	v_sqrt_f32_e32 v1, v0
	s_nop 0
	v_add_u32_e32 v132, -1, v1
	v_fma_f32 v133, -v132, v1, v0
	v_cmp_ge_f32_e64 s[4:5], 0, v133
	v_add_u32_e32 v133, 1, v1
	s_nop 0
	v_cndmask_b32_e64 v132, v1, v132, s[4:5]
	v_fma_f32 v1, -v133, v1, v0
	v_cmp_lt_f32_e64 s[4:5], 0, v1
	s_nop 1
	v_cndmask_b32_e64 v1, v132, v133, s[4:5]
	v_mul_f32_e32 v132, 0x37800000, v1
	v_cndmask_b32_e32 v1, v1, v132, vcc
	v_mov_b32_e32 v132, 0x260
	v_cmp_class_f32_e32 vcc, v0, v132
	s_nop 1
	v_cndmask_b32_e32 v0, v1, v0, vcc
	v_div_scale_f32 v1, s[2:3], v0, v0, 1.0
	v_rcp_f32_e32 v132, v1
	s_nop 0
	v_fma_f32 v133, -v1, v132, 1.0
	v_fmac_f32_e32 v132, v133, v132
	v_div_scale_f32 v133, vcc, 1.0, v0, 1.0
	v_mul_f32_e32 v134, v133, v132
	v_fma_f32 v135, -v1, v134, v133
	v_fmac_f32_e32 v134, v135, v132
	v_fma_f32 v1, -v1, v134, v133
	v_div_fmas_f32 v1, v1, v132, v134
	v_div_fixup_f32 v139, v1, v0, 1.0
	v_lshl_add_u32 v0, v2, 3, 0
	ds_write_b64 v0, v[138:139] offset:8192
.LBB0_1187:
	s_or_b64 exec, exec, s[6:7]
	v_ashrrev_i32_e32 v141, 31, v140
	v_readlane_b32 s2, v254, 21
	v_lshlrev_b64 v[132:133], 2, v[140:141]
	v_readlane_b32 s3, v254, 22
	s_waitcnt lgkmcnt(0)
	s_barrier
	v_lshl_add_u32 v157, s1, 18, v140
	v_lshl_add_u64 v[0:1], s[2:3], 0, v[132:133]
	v_readlane_b32 s2, v254, 23
	v_readlane_b32 s3, v254, 24
	global_load_dwordx4 v[186:189], v[0:1], off
	v_lshlrev_b32_e32 v2, 10, v144
	v_lshl_add_u64 v[148:149], s[2:3], 0, v[132:133]
	global_load_dwordx4 v[190:193], v[148:149], off
	global_load_dwordx4 v[204:207], v[0:1], off offset:64
	global_load_dwordx4 v[208:211], v[148:149], off offset:64
	global_load_dwordx4 v[212:215], v[0:1], off offset:512
	global_load_dwordx4 v[216:219], v[148:149], off offset:512
	global_load_dwordx4 v[220:223], v[0:1], off offset:576
	global_load_dwordx4 v[224:227], v[148:149], off offset:576
	s_lshl_b32 s2, s0, 9
	s_add_i32 s1, s2, 0
	v_lshl_add_u32 v132, v144, 3, s1
	v_add_u32_e32 v132, 0x2000, v132
	v_lshl_or_b32 v151, s0, 16, v2
	ds_read2_b64 v[144:147], v132 offset1:16
	ds_read2_b64 v[140:143], v132 offset0:32 offset1:48
	ds_read2_b64 v[136:139], v132 offset0:128 offset1:144
	ds_read2_b64 v[132:135], v132 offset0:160 offset1:176
	v_add_u32_e32 v2, v157, v151
	v_or_b32_e32 v152, 0x4000, v151
	v_or_b32_e32 v153, 0x8000, v151
	v_lshl_add_u64 v[168:169], v[2:3], 2, s[40:41]
	v_add_u32_e32 v2, v157, v152
	v_or_b32_e32 v154, 0xc000, v151
	v_lshl_add_u64 v[176:177], v[2:3], 2, s[40:41]
	v_add_u32_e32 v2, v157, v153
	s_waitcnt lgkmcnt(3)
	v_sub_f32_e32 v39, v39, v144
	v_sub_f32_e32 v38, v38, v144
	v_sub_f32_e32 v37, v37, v144
	v_sub_f32_e32 v36, v36, v144
	v_add_u32_e32 v150, 0x20000, v151
	v_lshl_add_u64 v[178:179], v[2:3], 2, s[40:41]
	v_add_u32_e32 v2, v157, v154
	v_sub_f32_e32 v43, v43, v146
	v_sub_f32_e32 v42, v42, v146
	v_sub_f32_e32 v41, v41, v146
	v_sub_f32_e32 v40, v40, v146
	s_waitcnt lgkmcnt(2)
	v_sub_f32_e32 v103, v103, v140
	v_sub_f32_e32 v102, v102, v140
	v_sub_f32_e32 v101, v101, v140
	v_sub_f32_e32 v100, v100, v140
	v_sub_f32_e32 v107, v107, v142
	v_sub_f32_e32 v106, v106, v142
	v_sub_f32_e32 v105, v105, v142
	v_sub_f32_e32 v104, v104, v142
	s_waitcnt lgkmcnt(1)
	v_sub_f32_e32 v131, v131, v136
	v_sub_f32_e32 v130, v130, v136
	v_sub_f32_e32 v129, v129, v136
	v_sub_f32_e32 v128, v128, v136
	v_pk_mul_f32 v[36:37], v[144:145], v[36:37] op_sel:[1,0]
	v_pk_mul_f32 v[38:39], v[144:145], v[38:39] op_sel:[1,0]
	v_add_u32_e32 v155, 0x24000, v151
	v_lshl_add_u64 v[194:195], v[2:3], 2, s[40:41]
	v_add_u32_e32 v2, v157, v150
	v_sub_f32_e32 v199, v123, v138
	v_sub_f32_e32 v198, v122, v138
	v_sub_f32_e32 v201, v121, v138
	v_sub_f32_e32 v200, v120, v138
	v_pk_mul_f32 v[40:41], v[146:147], v[40:41] op_sel:[1,0]
	v_pk_mul_f32 v[42:43], v[146:147], v[42:43] op_sel:[1,0]
	v_pk_mul_f32 v[100:101], v[140:141], v[100:101] op_sel:[1,0]
	v_pk_mul_f32 v[102:103], v[140:141], v[102:103] op_sel:[1,0]
	v_pk_mul_f32 v[104:105], v[142:143], v[104:105] op_sel:[1,0]
	v_pk_mul_f32 v[106:107], v[142:143], v[106:107] op_sel:[1,0]
	v_pk_mul_f32 v[120:121], v[136:137], v[128:129] op_sel:[1,0]
	v_pk_mul_f32 v[122:123], v[136:137], v[130:131] op_sel:[1,0]
	v_lshl_add_u64 v[196:197], v[2:3], 2, s[40:41]
	v_add_u32_e32 v2, v157, v155
	v_sub_f32_e32 v23, v23, v144
	v_sub_f32_e32 v22, v22, v144
	v_sub_f32_e32 v21, v21, v144
	v_sub_f32_e32 v20, v20, v144
	v_sub_f32_e32 v27, v27, v146
	v_sub_f32_e32 v26, v26, v146
	v_sub_f32_e32 v25, v25, v146
	v_sub_f32_e32 v24, v24, v146
	v_pk_mul_f32 v[20:21], v[144:145], v[20:21] op_sel:[1,0]
	v_pk_mul_f32 v[22:23], v[144:145], v[22:23] op_sel:[1,0]
	v_pk_mul_f32 v[24:25], v[146:147], v[24:25] op_sel:[1,0]
	v_pk_mul_f32 v[26:27], v[146:147], v[26:27] op_sel:[1,0]
	v_sub_f32_e32 v15, v15, v144
	v_sub_f32_e32 v14, v14, v144
	v_sub_f32_e32 v13, v13, v144
	v_sub_f32_e32 v12, v12, v144
	v_sub_f32_e32 v17, v17, v146
	v_sub_f32_e32 v16, v16, v146
	v_sub_f32_e32 v19, v19, v146
	v_sub_f32_e32 v18, v18, v146
	v_pk_mul_f32 v[12:13], v[144:145], v[12:13] op_sel:[1,0]
	v_pk_mul_f32 v[14:15], v[144:145], v[14:15] op_sel:[1,0]
	v_pk_mul_f32 v[16:17], v[146:147], v[16:17] op_sel:[1,0]
	s_waitcnt vmcnt(0)
	v_pk_fma_f32 v[38:39], v[38:39], v[188:189], v[192:193]
	v_pk_fma_f32 v[36:37], v[36:37], v[186:187], v[190:191]
	v_pk_fma_f32 v[42:43], v[42:43], v[188:189], v[192:193]
	v_pk_fma_f32 v[40:41], v[40:41], v[186:187], v[190:191]
	v_pk_fma_f32 v[102:103], v[102:103], v[188:189], v[192:193]
	v_pk_fma_f32 v[100:101], v[100:101], v[186:187], v[190:191]
	v_pk_fma_f32 v[106:107], v[106:107], v[188:189], v[192:193]
	v_pk_fma_f32 v[104:105], v[104:105], v[186:187], v[190:191]
	v_pk_fma_f32 v[122:123], v[122:123], v[188:189], v[192:193]
	v_pk_fma_f32 v[120:121], v[120:121], v[186:187], v[190:191]
	global_store_dwordx4 v[168:169], v[36:39], off
	global_store_dwordx4 v[176:177], v[40:43], off
	global_store_dwordx4 v[178:179], v[100:103], off
	global_store_dwordx4 v[194:195], v[104:107], off
	global_store_dwordx4 v[196:197], v[120:123], off
	v_pk_mul_f32 v[36:37], v[138:139], v[200:201] op_sel:[1,0]
	v_pk_mul_f32 v[38:39], v[138:139], v[198:199] op_sel:[1,0]
	v_pk_fma_f32 v[36:37], v[186:187], v[36:37], v[190:191]
	v_pk_fma_f32 v[38:39], v[188:189], v[38:39], v[192:193]
	v_lshl_add_u64 v[40:41], v[2:3], 2, s[40:41]
	global_store_dwordx4 v[40:41], v[36:39], off
	s_waitcnt lgkmcnt(0)
	v_sub_f32_e32 v41, v81, v132
	v_sub_f32_e32 v40, v80, v132
	v_add_u32_e32 v36, 0x28000, v151
	v_sub_f32_e32 v39, v83, v132
	v_sub_f32_e32 v38, v82, v132
	v_add_u32_e32 v2, v157, v36
	v_pk_mul_f32 v[42:43], v[132:133], v[40:41] op_sel:[1,0]
	v_pk_mul_f32 v[38:39], v[132:133], v[38:39] op_sel:[1,0]
	v_add_u32_e32 v37, 0x2c000, v151
	v_pk_fma_f32 v[40:41], v[188:189], v[38:39], v[192:193]
	v_pk_fma_f32 v[38:39], v[186:187], v[42:43], v[190:191]
	v_lshl_add_u64 v[42:43], v[2:3], 2, s[40:41]
	global_store_dwordx4 v[42:43], v[38:41], off
	v_add_u32_e32 v2, v157, v37
	v_or_b32_e32 v120, 16, v157
	v_sub_f32_e32 v39, v75, v134
	v_sub_f32_e32 v38, v74, v134
	v_sub_f32_e32 v41, v73, v134
	v_sub_f32_e32 v40, v72, v134
	v_pk_mul_f32 v[42:43], v[134:135], v[40:41] op_sel:[1,0]
	v_pk_mul_f32 v[38:39], v[134:135], v[38:39] op_sel:[1,0]
	v_sub_f32_e32 v81, v85, v140
	v_pk_fma_f32 v[40:41], v[188:189], v[38:39], v[192:193]
	v_pk_fma_f32 v[38:39], v[186:187], v[42:43], v[190:191]
	v_lshl_add_u64 v[42:43], v[2:3], 2, s[40:41]
	global_store_dwordx4 v[42:43], v[38:41], off
	s_nop 1
	v_mov_b32_e32 v38, v204
	v_mov_b32_e32 v39, v205
	v_mov_b32_e32 v40, v206
	v_mov_b32_e32 v41, v207
	s_nop 0
	s_nop 1
	v_mov_b32_e32 v72, v208
	v_mov_b32_e32 v73, v209
	v_mov_b32_e32 v74, v210
	v_mov_b32_e32 v75, v211
	v_add_u32_e32 v2, v120, v151
	v_lshl_add_u64 v[100:101], v[2:3], 2, s[40:41]
	v_add_u32_e32 v2, v120, v152
	v_sub_f32_e32 v43, v87, v140
	v_sub_f32_e32 v42, v86, v140
	v_sub_f32_e32 v80, v84, v140
	v_sub_f32_e32 v83, v91, v142
	v_sub_f32_e32 v82, v90, v142
	v_sub_f32_e32 v85, v89, v142
	v_sub_f32_e32 v84, v88, v142
	v_lshl_add_u64 v[102:103], v[2:3], 2, s[40:41]
	v_add_u32_e32 v2, v120, v153
	v_sub_f32_e32 v89, v127, v136
	v_sub_f32_e32 v88, v126, v136
	v_sub_f32_e32 v91, v125, v136
	v_sub_f32_e32 v90, v124, v136
	v_pk_mul_f32 v[80:81], v[140:141], v[80:81] op_sel:[1,0]
	v_pk_mul_f32 v[42:43], v[140:141], v[42:43] op_sel:[1,0]
	v_pk_mul_f32 v[84:85], v[142:143], v[84:85] op_sel:[1,0]
	v_pk_mul_f32 v[86:87], v[142:143], v[82:83] op_sel:[1,0]
	v_lshl_add_u64 v[104:105], v[2:3], 2, s[40:41]
	v_add_u32_e32 v2, v120, v154
	v_lshl_add_u64 v[106:107], v[2:3], 2, s[40:41]
	v_add_u32_e32 v2, v120, v150
	v_pk_mul_f32 v[18:19], v[146:147], v[18:19] op_sel:[1,0]
	v_sub_f32_e32 v5, v5, v144
	v_sub_f32_e32 v4, v4, v144
	v_sub_f32_e32 v9, v9, v146
	v_sub_f32_e32 v8, v8, v146
	v_pk_mul_f32 v[4:5], v[144:145], v[4:5] op_sel:[1,0]
	v_pk_mul_f32 v[8:9], v[146:147], v[8:9] op_sel:[1,0]
	v_pk_fma_f32 v[22:23], v[22:23], v[40:41], v[74:75]
	v_pk_fma_f32 v[20:21], v[20:21], v[38:39], v[72:73]
	v_pk_fma_f32 v[26:27], v[26:27], v[40:41], v[74:75]
	v_pk_fma_f32 v[24:25], v[24:25], v[38:39], v[72:73]
	v_pk_fma_f32 v[82:83], v[42:43], v[40:41], v[74:75]
	v_pk_fma_f32 v[80:81], v[80:81], v[38:39], v[72:73]
	v_pk_fma_f32 v[86:87], v[86:87], v[40:41], v[74:75]
	v_pk_fma_f32 v[84:85], v[84:85], v[38:39], v[72:73]
	global_store_dwordx4 v[100:101], v[20:23], off
	global_store_dwordx4 v[102:103], v[24:27], off
	global_store_dwordx4 v[104:105], v[80:83], off
	global_store_dwordx4 v[106:107], v[84:87], off
	v_pk_mul_f32 v[20:21], v[136:137], v[90:91] op_sel:[1,0]
	v_pk_mul_f32 v[22:23], v[136:137], v[88:89] op_sel:[1,0]
	v_pk_fma_f32 v[20:21], v[20:21], v[38:39], v[72:73]
	v_pk_fma_f32 v[22:23], v[22:23], v[40:41], v[74:75]
	v_lshl_add_u64 v[24:25], v[2:3], 2, s[40:41]
	global_store_dwordx4 v[24:25], v[20:23], off
	v_add_u32_e32 v2, v120, v155
	v_sub_f32_e32 v43, v71, v142
	v_sub_f32_e32 v21, v119, v138
	v_sub_f32_e32 v20, v118, v138
	v_sub_f32_e32 v23, v117, v138
	v_sub_f32_e32 v22, v116, v138
	v_pk_mul_f32 v[24:25], v[138:139], v[22:23] op_sel:[1,0]
	v_pk_mul_f32 v[20:21], v[138:139], v[20:21] op_sel:[1,0]
	v_sub_f32_e32 v42, v70, v142
	v_pk_fma_f32 v[22:23], v[20:21], v[40:41], v[74:75]
	v_pk_fma_f32 v[20:21], v[24:25], v[38:39], v[72:73]
	v_lshl_add_u64 v[24:25], v[2:3], 2, s[40:41]
	global_store_dwordx4 v[24:25], v[20:23], off
	v_add_u32_e32 v2, v120, v36
	v_pk_mul_f32 v[42:43], v[142:143], v[42:43] op_sel:[1,0]
	v_sub_f32_e32 v21, v79, v132
	v_sub_f32_e32 v20, v78, v132
	v_sub_f32_e32 v23, v77, v132
	v_sub_f32_e32 v22, v76, v132
	v_pk_mul_f32 v[24:25], v[132:133], v[22:23] op_sel:[1,0]
	v_pk_mul_f32 v[20:21], v[132:133], v[20:21] op_sel:[1,0]
	s_nop 0
	v_pk_fma_f32 v[22:23], v[20:21], v[40:41], v[74:75]
	v_pk_fma_f32 v[20:21], v[24:25], v[38:39], v[72:73]
	v_lshl_add_u64 v[24:25], v[2:3], 2, s[40:41]
	global_store_dwordx4 v[24:25], v[20:23], off
	v_add_u32_e32 v2, v120, v37
	s_nop 0
	v_sub_f32_e32 v21, v63, v134
	v_sub_f32_e32 v20, v62, v134
	v_sub_f32_e32 v23, v61, v134
	v_sub_f32_e32 v22, v60, v134
	v_pk_mul_f32 v[24:25], v[134:135], v[22:23] op_sel:[1,0]
	v_pk_mul_f32 v[20:21], v[134:135], v[20:21] op_sel:[1,0]
	v_sub_f32_e32 v61, v69, v142
	v_pk_fma_f32 v[22:23], v[20:21], v[40:41], v[74:75]
	v_pk_fma_f32 v[20:21], v[24:25], v[38:39], v[72:73]
	v_lshl_add_u64 v[24:25], v[2:3], 2, s[40:41]
	global_store_dwordx4 v[24:25], v[20:23], off
	s_nop 1
	v_mov_b32_e32 v20, v212
	v_mov_b32_e32 v21, v213
	v_mov_b32_e32 v22, v214
	v_mov_b32_e32 v23, v215
	s_nop 0
	s_nop 1
	v_mov_b32_e32 v24, v216
	v_mov_b32_e32 v25, v217
	v_mov_b32_e32 v26, v218
	v_mov_b32_e32 v27, v219
	v_or_b32_e32 v72, 0x80, v157
	v_add_u32_e32 v2, v72, v151
	v_sub_f32_e32 v41, v65, v140
	v_sub_f32_e32 v40, v64, v140
	v_lshl_add_u64 v[64:65], v[2:3], 2, s[40:41]
	v_add_u32_e32 v2, v72, v152
	v_sub_f32_e32 v39, v67, v140
	v_sub_f32_e32 v38, v66, v140
	v_sub_f32_e32 v60, v68, v142
	v_lshl_add_u64 v[66:67], v[2:3], 2, s[40:41]
	v_add_u32_e32 v2, v72, v153
	v_pk_mul_f32 v[62:63], v[140:141], v[40:41] op_sel:[1,0]
	v_pk_mul_f32 v[38:39], v[140:141], v[38:39] op_sel:[1,0]
	v_pk_mul_f32 v[60:61], v[142:143], v[60:61] op_sel:[1,0]
	v_lshl_add_u64 v[68:69], v[2:3], 2, s[40:41]
	v_add_u32_e32 v2, v72, v154
	v_pk_fma_f32 v[14:15], v[14:15], v[22:23], v[26:27]
	v_pk_fma_f32 v[12:13], v[12:13], v[20:21], v[24:25]
	v_pk_fma_f32 v[16:17], v[16:17], v[20:21], v[24:25]
	v_pk_fma_f32 v[18:19], v[18:19], v[22:23], v[26:27]
	v_pk_fma_f32 v[40:41], v[38:39], v[22:23], v[26:27]
	v_pk_fma_f32 v[38:39], v[62:63], v[20:21], v[24:25]
	global_store_dwordx4 v[64:65], v[12:15], off
	global_store_dwordx4 v[66:67], v[16:19], off
	global_store_dwordx4 v[68:69], v[38:41], off
	v_pk_fma_f32 v[14:15], v[42:43], v[22:23], v[26:27]
	v_pk_fma_f32 v[12:13], v[60:61], v[20:21], v[24:25]
	v_lshl_add_u64 v[16:17], v[2:3], 2, s[40:41]
	global_store_dwordx4 v[16:17], v[12:15], off
	v_add_u32_e32 v2, v72, v150
	v_or_b32_e32 v38, 0x90, v157
	v_sub_f32_e32 v13, v111, v136
	v_sub_f32_e32 v12, v110, v136
	v_sub_f32_e32 v15, v109, v136
	v_sub_f32_e32 v14, v108, v136
	v_pk_mul_f32 v[16:17], v[136:137], v[14:15] op_sel:[1,0]
	v_pk_mul_f32 v[12:13], v[136:137], v[12:13] op_sel:[1,0]
	s_nop 0
	v_pk_fma_f32 v[14:15], v[12:13], v[22:23], v[26:27]
	v_pk_fma_f32 v[12:13], v[16:17], v[20:21], v[24:25]
	v_lshl_add_u64 v[16:17], v[2:3], 2, s[40:41]
	global_store_dwordx4 v[16:17], v[12:15], off
	v_add_u32_e32 v2, v72, v155
	s_nop 0
	v_sub_f32_e32 v13, v115, v138
	v_sub_f32_e32 v12, v114, v138
	v_sub_f32_e32 v15, v113, v138
	v_sub_f32_e32 v14, v112, v138
	v_pk_mul_f32 v[16:17], v[138:139], v[14:15] op_sel:[1,0]
	v_pk_mul_f32 v[12:13], v[138:139], v[12:13] op_sel:[1,0]
	s_nop 0
	v_pk_fma_f32 v[14:15], v[12:13], v[22:23], v[26:27]
	v_pk_fma_f32 v[12:13], v[16:17], v[20:21], v[24:25]
	v_lshl_add_u64 v[16:17], v[2:3], 2, s[40:41]
	global_store_dwordx4 v[16:17], v[12:15], off
	v_add_u32_e32 v2, v72, v36
	s_nop 0
	v_sub_f32_e32 v13, v59, v132
	v_sub_f32_e32 v12, v58, v132
	v_sub_f32_e32 v15, v57, v132
	v_sub_f32_e32 v14, v56, v132
	v_pk_mul_f32 v[16:17], v[132:133], v[14:15] op_sel:[1,0]
	v_pk_mul_f32 v[12:13], v[132:133], v[12:13] op_sel:[1,0]
	s_nop 0
	v_pk_fma_f32 v[14:15], v[12:13], v[22:23], v[26:27]
	v_pk_fma_f32 v[12:13], v[16:17], v[20:21], v[24:25]
	v_lshl_add_u64 v[16:17], v[2:3], 2, s[40:41]
	global_store_dwordx4 v[16:17], v[12:15], off
	v_add_u32_e32 v2, v72, v37
	s_nop 0
	v_sub_f32_e32 v13, v51, v134
	v_sub_f32_e32 v12, v50, v134
	v_sub_f32_e32 v15, v49, v134
	v_sub_f32_e32 v14, v48, v134
	v_pk_mul_f32 v[16:17], v[134:135], v[14:15] op_sel:[1,0]
	v_pk_mul_f32 v[12:13], v[134:135], v[12:13] op_sel:[1,0]
	s_nop 0
	v_pk_fma_f32 v[14:15], v[12:13], v[22:23], v[26:27]
	v_pk_fma_f32 v[12:13], v[16:17], v[20:21], v[24:25]
	v_lshl_add_u64 v[16:17], v[2:3], 2, s[40:41]
	global_store_dwordx4 v[16:17], v[12:15], off
	s_nop 1
	v_mov_b32_e32 v12, v220
	v_mov_b32_e32 v13, v221
	v_mov_b32_e32 v14, v222
	v_mov_b32_e32 v15, v223
	s_nop 0
	s_nop 1
	v_mov_b32_e32 v16, v224
	v_mov_b32_e32 v17, v225
	v_mov_b32_e32 v18, v226
	v_mov_b32_e32 v19, v227
	v_add_u32_e32 v2, v38, v151
	v_sub_f32_e32 v1, v7, v144
	v_sub_f32_e32 v0, v6, v144
	v_sub_f32_e32 v7, v11, v146
	v_sub_f32_e32 v6, v10, v146
	v_sub_f32_e32 v11, v35, v140
	v_sub_f32_e32 v10, v34, v140
	v_sub_f32_e32 v21, v33, v140
	v_sub_f32_e32 v20, v32, v140
	v_lshl_add_u64 v[26:27], v[2:3], 2, s[40:41]
	v_add_u32_e32 v2, v38, v152
	v_pk_mul_f32 v[0:1], v[144:145], v[0:1] op_sel:[1,0]
	v_pk_mul_f32 v[22:23], v[146:147], v[6:7] op_sel:[1,0]
	v_pk_mul_f32 v[20:21], v[140:141], v[20:21] op_sel:[1,0]
	v_pk_mul_f32 v[24:25], v[140:141], v[10:11] op_sel:[1,0]
	v_lshl_add_u64 v[32:33], v[2:3], 2, s[40:41]
	v_add_u32_e32 v2, v38, v153
	v_pk_fma_f32 v[6:7], v[0:1], v[14:15], v[18:19]
	v_pk_fma_f32 v[4:5], v[4:5], v[12:13], v[16:17]
	v_pk_fma_f32 v[10:11], v[22:23], v[14:15], v[18:19]
	v_pk_fma_f32 v[22:23], v[24:25], v[14:15], v[18:19]
	v_pk_fma_f32 v[20:21], v[20:21], v[12:13], v[16:17]
	v_lshl_add_u64 v[0:1], v[2:3], 2, s[40:41]
	v_pk_fma_f32 v[8:9], v[8:9], v[12:13], v[16:17]
	global_store_dwordx4 v[26:27], v[4:7], off
	global_store_dwordx4 v[32:33], v[8:11], off
	global_store_dwordx4 v[0:1], v[20:23], off
	v_sub_f32_e32 v1, v31, v142
	v_sub_f32_e32 v0, v30, v142
	v_sub_f32_e32 v5, v29, v142
	v_sub_f32_e32 v4, v28, v142
	v_add_u32_e32 v2, v38, v154
	v_pk_mul_f32 v[4:5], v[142:143], v[4:5] op_sel:[1,0]
	v_pk_mul_f32 v[0:1], v[142:143], v[0:1] op_sel:[1,0]
	v_pk_fma_f32 v[4:5], v[4:5], v[12:13], v[16:17]
	v_pk_fma_f32 v[6:7], v[0:1], v[14:15], v[18:19]
	v_lshl_add_u64 v[0:1], v[2:3], 2, s[40:41]
	global_store_dwordx4 v[0:1], v[4:7], off
	v_sub_f32_e32 v1, v95, v136
	v_sub_f32_e32 v0, v94, v136
	v_sub_f32_e32 v5, v93, v136
	v_sub_f32_e32 v4, v92, v136
	v_add_u32_e32 v2, v38, v150
	v_pk_mul_f32 v[4:5], v[136:137], v[4:5] op_sel:[1,0]
	v_pk_mul_f32 v[0:1], v[136:137], v[0:1] op_sel:[1,0]
	v_pk_fma_f32 v[4:5], v[4:5], v[12:13], v[16:17]
	v_pk_fma_f32 v[6:7], v[0:1], v[14:15], v[18:19]
	v_lshl_add_u64 v[0:1], v[2:3], 2, s[40:41]
	global_store_dwordx4 v[0:1], v[4:7], off
	v_sub_f32_e32 v1, v99, v138
	v_sub_f32_e32 v0, v98, v138
	v_sub_f32_e32 v5, v97, v138
	v_sub_f32_e32 v4, v96, v138
	v_add_u32_e32 v2, v38, v155
	v_pk_mul_f32 v[4:5], v[138:139], v[4:5] op_sel:[1,0]
	v_pk_mul_f32 v[0:1], v[138:139], v[0:1] op_sel:[1,0]
	v_pk_fma_f32 v[4:5], v[4:5], v[12:13], v[16:17]
	v_pk_fma_f32 v[6:7], v[0:1], v[14:15], v[18:19]
	v_lshl_add_u64 v[0:1], v[2:3], 2, s[40:41]
	global_store_dwordx4 v[0:1], v[4:7], off
	v_sub_f32_e32 v1, v55, v132
	v_sub_f32_e32 v0, v54, v132
	v_sub_f32_e32 v5, v53, v132
	v_sub_f32_e32 v4, v52, v132
	v_add_u32_e32 v2, v38, v36
	v_pk_mul_f32 v[4:5], v[132:133], v[4:5] op_sel:[1,0]
	v_pk_mul_f32 v[0:1], v[132:133], v[0:1] op_sel:[1,0]
	v_pk_fma_f32 v[4:5], v[4:5], v[12:13], v[16:17]
	v_pk_fma_f32 v[6:7], v[0:1], v[14:15], v[18:19]
	v_lshl_add_u64 v[0:1], v[2:3], 2, s[40:41]
	global_store_dwordx4 v[0:1], v[4:7], off
	v_sub_f32_e32 v1, v47, v134
	v_sub_f32_e32 v0, v46, v134
	v_sub_f32_e32 v5, v45, v134
	v_sub_f32_e32 v4, v44, v134
	v_add_u32_e32 v2, v38, v37
	v_pk_mul_f32 v[4:5], v[134:135], v[4:5] op_sel:[1,0]
	v_pk_mul_f32 v[0:1], v[134:135], v[0:1] op_sel:[1,0]
	v_pk_fma_f32 v[4:5], v[4:5], v[12:13], v[16:17]
	v_pk_fma_f32 v[6:7], v[0:1], v[14:15], v[18:19]
	v_lshl_add_u64 v[0:1], v[2:3], 2, s[40:41]
	global_store_dwordx4 v[0:1], v[4:7], off

.LBB0_1243:
	s_or_b64 exec, exec, s[6:7]
	v_ashrrev_i32_e32 v141, 31, v140
	v_readlane_b32 s2, v254, 25
	v_lshlrev_b64 v[132:133], 2, v[140:141]
	v_readlane_b32 s3, v254, 26
	s_waitcnt lgkmcnt(0)
	s_barrier
	v_lshl_add_u32 v183, s1, 18, v140
	v_lshl_add_u64 v[0:1], s[2:3], 0, v[132:133]
	v_readlane_b32 s2, v254, 27
	v_readlane_b32 s3, v254, 28
	global_load_dwordx4 v[148:151], v[0:1], off
	v_lshlrev_b32_e32 v2, 10, v144
	v_lshl_add_u64 v[168:169], s[2:3], 0, v[132:133]
	global_load_dwordx4 v[152:155], v[168:169], off
	global_load_dwordx4 v[200:203], v[0:1], off offset:64
	global_load_dwordx4 v[204:207], v[168:169], off offset:64
	global_load_dwordx4 v[208:211], v[0:1], off offset:512
	global_load_dwordx4 v[212:215], v[168:169], off offset:512
	global_load_dwordx4 v[216:219], v[0:1], off offset:576
	global_load_dwordx4 v[220:223], v[168:169], off offset:576
	s_lshl_b32 s2, s0, 9
	s_add_i32 s1, s2, 0
	v_lshl_add_u32 v132, v144, 3, s1
	v_add_u32_e32 v132, 0x2000, v132
	ds_read2_b64 v[144:147], v132 offset1:16
	ds_read2_b64 v[140:143], v132 offset0:32 offset1:48
	ds_read2_b64 v[136:139], v132 offset0:128 offset1:144
	ds_read2_b64 v[132:135], v132 offset0:160 offset1:176
	v_lshl_or_b32 v184, s0, 16, v2
	s_waitcnt lgkmcnt(3)
	v_sub_f32_e32 v39, v39, v144
	v_sub_f32_e32 v38, v38, v144
	v_sub_f32_e32 v37, v37, v144
	v_sub_f32_e32 v36, v36, v144
	v_sub_f32_e32 v43, v43, v146
	v_sub_f32_e32 v42, v42, v146
	v_sub_f32_e32 v41, v41, v146
	v_sub_f32_e32 v40, v40, v146
	s_waitcnt lgkmcnt(2)
	v_sub_f32_e32 v103, v103, v140
	v_sub_f32_e32 v102, v102, v140
	v_sub_f32_e32 v101, v101, v140
	v_sub_f32_e32 v100, v100, v140
	v_pk_mul_f32 v[36:37], v[144:145], v[36:37] op_sel:[1,0]
	v_pk_mul_f32 v[38:39], v[144:145], v[38:39] op_sel:[1,0]
	v_pk_mul_f32 v[40:41], v[146:147], v[40:41] op_sel:[1,0]
	v_pk_mul_f32 v[42:43], v[146:147], v[42:43] op_sel:[1,0]
	v_pk_mul_f32 v[100:101], v[140:141], v[100:101] op_sel:[1,0]
	v_pk_mul_f32 v[102:103], v[140:141], v[102:103] op_sel:[1,0]
	v_add_u32_e32 v2, v183, v184
	v_or_b32_e32 v187, 0x4000, v184
	v_or_b32_e32 v186, 0x8000, v184
	v_lshl_add_u64 v[176:177], v[2:3], 1, s[64:65]
	v_add_u32_e32 v2, v183, v187
	v_lshl_add_u64 v[178:179], v[2:3], 1, s[64:65]
	v_add_u32_e32 v2, v183, v186
	v_sub_f32_e32 v107, v107, v142
	v_sub_f32_e32 v106, v106, v142
	v_sub_f32_e32 v105, v105, v142
	v_sub_f32_e32 v104, v104, v142
	v_lshl_add_u64 v[188:189], v[2:3], 1, s[64:65]
	v_pk_mul_f32 v[104:105], v[142:143], v[104:105] op_sel:[1,0]
	v_pk_mul_f32 v[106:107], v[142:143], v[106:107] op_sel:[1,0]
	v_or_b32_e32 v185, 0xc000, v184
	v_add_u32_e32 v157, 0x20000, v184
	v_add_u32_e32 v2, v183, v185
	v_sub_f32_e32 v27, v27, v144
	v_sub_f32_e32 v26, v26, v144
	v_sub_f32_e32 v25, v25, v144
	v_sub_f32_e32 v24, v24, v144
	v_pk_mul_f32 v[24:25], v[144:145], v[24:25] op_sel:[1,0]
	v_pk_mul_f32 v[26:27], v[144:145], v[26:27] op_sel:[1,0]
	v_sub_f32_e32 v23, v23, v146
	v_sub_f32_e32 v22, v22, v146
	v_sub_f32_e32 v21, v21, v146
	v_sub_f32_e32 v20, v20, v146
	v_pk_mul_f32 v[20:21], v[146:147], v[20:21] op_sel:[1,0]
	v_pk_mul_f32 v[22:23], v[146:147], v[22:23] op_sel:[1,0]
	v_sub_f32_e32 v19, v19, v144
	v_sub_f32_e32 v18, v18, v144
	v_sub_f32_e32 v17, v17, v144
	v_sub_f32_e32 v16, v16, v144
	v_pk_mul_f32 v[16:17], v[144:145], v[16:17] op_sel:[1,0]
	v_pk_mul_f32 v[18:19], v[144:145], v[18:19] op_sel:[1,0]
	v_sub_f32_e32 v15, v15, v146
	v_sub_f32_e32 v14, v14, v146
	v_sub_f32_e32 v13, v13, v146
	v_sub_f32_e32 v12, v12, v146
	v_pk_mul_f32 v[12:13], v[146:147], v[12:13] op_sel:[1,0]
	v_pk_mul_f32 v[14:15], v[146:147], v[14:15] op_sel:[1,0]
	v_sub_f32_e32 v9, v9, v144
	v_sub_f32_e32 v8, v8, v144
	v_pk_mul_f32 v[8:9], v[144:145], v[8:9] op_sel:[1,0]
	v_sub_f32_e32 v7, v7, v146
	v_sub_f32_e32 v6, v6, v146
	v_pk_mul_f32 v[6:7], v[146:147], v[6:7] op_sel:[1,0]
	v_sub_f32_e32 v5, v5, v146
	v_sub_f32_e32 v4, v4, v146
	v_pk_mul_f32 v[4:5], v[146:147], v[4:5] op_sel:[1,0]
	s_waitcnt vmcnt(0)
	v_pk_fma_f32 v[38:39], v[38:39], v[150:151], v[154:155]
	v_pk_fma_f32 v[36:37], v[36:37], v[148:149], v[152:153]
	v_pk_fma_f32 v[42:43], v[42:43], v[150:151], v[154:155]
	v_pk_fma_f32 v[40:41], v[40:41], v[148:149], v[152:153]
	v_pk_fma_f32 v[102:103], v[102:103], v[150:151], v[154:155]
	v_pk_fma_f32 v[100:101], v[100:101], v[148:149], v[152:153]
	v_cvt_f16_f32_e32 v36, v36
	v_cvt_f16_f32_sdwa v37, v37 dst_sel:WORD_1 dst_unused:UNUSED_PAD src0_sel:DWORD
	v_cvt_f16_f32_e32 v38, v38
	v_cvt_f16_f32_sdwa v39, v39 dst_sel:WORD_1 dst_unused:UNUSED_PAD src0_sel:DWORD
	v_cvt_f16_f32_e32 v40, v40
	v_cvt_f16_f32_sdwa v41, v41 dst_sel:WORD_1 dst_unused:UNUSED_PAD src0_sel:DWORD
	v_cvt_f16_f32_e32 v42, v42
	v_cvt_f16_f32_sdwa v43, v43 dst_sel:WORD_1 dst_unused:UNUSED_PAD src0_sel:DWORD
	v_cvt_f16_f32_e32 v100, v100
	v_cvt_f16_f32_sdwa v101, v101 dst_sel:WORD_1 dst_unused:UNUSED_PAD src0_sel:DWORD
	v_cvt_f16_f32_e32 v102, v102
	v_cvt_f16_f32_sdwa v103, v103 dst_sel:WORD_1 dst_unused:UNUSED_PAD src0_sel:DWORD
	v_or_b32_e32 v36, v37, v36
	v_or_b32_e32 v37, v39, v38
	v_or_b32_e32 v38, v41, v40
	v_or_b32_e32 v39, v43, v42
	v_or_b32_e32 v40, v101, v100
	v_or_b32_e32 v41, v103, v102
	global_store_dwordx2 v[176:177], v[36:37], off
	global_store_dwordx2 v[178:179], v[38:39], off
	global_store_dwordx2 v[188:189], v[40:41], off
	s_waitcnt lgkmcnt(1)
	v_sub_f32_e32 v39, v131, v136
	v_sub_f32_e32 v38, v130, v136
	v_sub_f32_e32 v41, v129, v136
	v_sub_f32_e32 v40, v128, v136
	v_pk_fma_f32 v[106:107], v[106:107], v[150:151], v[154:155]
	v_pk_fma_f32 v[104:105], v[104:105], v[148:149], v[152:153]
	v_pk_mul_f32 v[40:41], v[136:137], v[40:41] op_sel:[1,0]
	v_pk_mul_f32 v[38:39], v[136:137], v[38:39] op_sel:[1,0]
	v_cvt_f16_f32_e32 v104, v104
	v_cvt_f16_f32_sdwa v105, v105 dst_sel:WORD_1 dst_unused:UNUSED_PAD src0_sel:DWORD
	v_cvt_f16_f32_e32 v106, v106
	v_cvt_f16_f32_sdwa v107, v107 dst_sel:WORD_1 dst_unused:UNUSED_PAD src0_sel:DWORD
	v_pk_fma_f32 v[38:39], v[38:39], v[150:151], v[154:155]
	v_pk_fma_f32 v[40:41], v[40:41], v[148:149], v[152:153]
	v_cvt_f16_f32_e32 v38, v38
	v_cvt_f16_f32_e32 v40, v40
	v_cvt_f16_f32_sdwa v41, v41 dst_sel:WORD_1 dst_unused:UNUSED_PAD src0_sel:DWORD
	v_cvt_f16_f32_sdwa v39, v39 dst_sel:WORD_1 dst_unused:UNUSED_PAD src0_sel:DWORD
	v_or_b32_e32 v42, v105, v104
	v_or_b32_e32 v43, v107, v106
	v_lshl_add_u64 v[36:37], v[2:3], 1, s[64:65]
	v_add_u32_e32 v2, v183, v157
	global_store_dwordx2 v[36:37], v[42:43], off
	v_or_b32_e32 v36, v41, v40
	v_or_b32_e32 v37, v39, v38
	v_lshl_add_u64 v[38:39], v[2:3], 1, s[64:65]
	global_store_dwordx2 v[38:39], v[36:37], off
	v_sub_f32_e32 v37, v123, v138
	v_sub_f32_e32 v36, v122, v138
	v_sub_f32_e32 v39, v121, v138
	v_sub_f32_e32 v38, v120, v138
	v_pk_mul_f32 v[38:39], v[138:139], v[38:39] op_sel:[1,0]
	v_pk_mul_f32 v[36:37], v[138:139], v[36:37] op_sel:[1,0]
	v_pk_fma_f32 v[38:39], v[148:149], v[38:39], v[152:153]
	v_pk_fma_f32 v[36:37], v[150:151], v[36:37], v[154:155]
	v_cvt_f16_f32_e32 v38, v38
	v_cvt_f16_f32_sdwa v39, v39 dst_sel:WORD_1 dst_unused:UNUSED_PAD src0_sel:DWORD
	v_cvt_f16_f32_e32 v40, v36
	v_cvt_f16_f32_sdwa v37, v37 dst_sel:WORD_1 dst_unused:UNUSED_PAD src0_sel:DWORD
	v_add_u32_e32 v36, 0x24000, v184
	v_add_u32_e32 v2, v183, v36
	v_or_b32_e32 v38, v39, v38
	v_or_b32_e32 v39, v37, v40
	v_lshl_add_u64 v[40:41], v[2:3], 1, s[64:65]
	global_store_dwordx2 v[40:41], v[38:39], off
	s_waitcnt lgkmcnt(0)
	v_sub_f32_e32 v39, v83, v132
	v_sub_f32_e32 v38, v82, v132
	v_sub_f32_e32 v41, v81, v132
	v_sub_f32_e32 v40, v80, v132
	v_pk_mul_f32 v[40:41], v[132:133], v[40:41] op_sel:[1,0]
	v_pk_mul_f32 v[38:39], v[132:133], v[38:39] op_sel:[1,0]
	v_pk_fma_f32 v[40:41], v[148:149], v[40:41], v[152:153]
	v_pk_fma_f32 v[38:39], v[150:151], v[38:39], v[154:155]
	v_cvt_f16_f32_e32 v40, v40
	v_cvt_f16_f32_sdwa v41, v41 dst_sel:WORD_1 dst_unused:UNUSED_PAD src0_sel:DWORD
	v_cvt_f16_f32_e32 v42, v38
	v_cvt_f16_f32_sdwa v39, v39 dst_sel:WORD_1 dst_unused:UNUSED_PAD src0_sel:DWORD
	v_add_u32_e32 v37, 0x28000, v184
	v_add_u32_e32 v2, v183, v37
	v_or_b32_e32 v38, v41, v40
	v_or_b32_e32 v39, v39, v42
	v_lshl_add_u64 v[40:41], v[2:3], 1, s[64:65]
	global_store_dwordx2 v[40:41], v[38:39], off
	v_sub_f32_e32 v39, v75, v134
	v_sub_f32_e32 v38, v74, v134
	v_sub_f32_e32 v41, v73, v134
	v_sub_f32_e32 v40, v72, v134
	v_pk_mul_f32 v[40:41], v[134:135], v[40:41] op_sel:[1,0]
	v_pk_mul_f32 v[38:39], v[134:135], v[38:39] op_sel:[1,0]
	v_pk_fma_f32 v[40:41], v[148:149], v[40:41], v[152:153]
	v_pk_fma_f32 v[38:39], v[150:151], v[38:39], v[154:155]
	v_cvt_f16_f32_e32 v40, v40
	v_cvt_f16_f32_sdwa v41, v41 dst_sel:WORD_1 dst_unused:UNUSED_PAD src0_sel:DWORD
	v_cvt_f16_f32_e32 v42, v38
	v_cvt_f16_f32_sdwa v39, v39 dst_sel:WORD_1 dst_unused:UNUSED_PAD src0_sel:DWORD
	v_add_u32_e32 v38, 0x2c000, v184
	v_add_u32_e32 v2, v183, v38
	v_or_b32_e32 v40, v41, v40
	v_or_b32_e32 v41, v39, v42
	v_lshl_add_u64 v[42:43], v[2:3], 1, s[64:65]
	global_store_dwordx2 v[42:43], v[40:41], off
	s_nop 1
	v_mov_b32_e32 v40, v200
	v_mov_b32_e32 v41, v201
	v_mov_b32_e32 v42, v202
	v_mov_b32_e32 v43, v203
	s_nop 0
	s_nop 1
	v_mov_b32_e32 v72, v204
	v_mov_b32_e32 v73, v205
	v_mov_b32_e32 v74, v206
	v_mov_b32_e32 v75, v207
	v_or_b32_e32 v39, 16, v183
	v_add_u32_e32 v2, v39, v184
	v_pk_fma_f32 v[26:27], v[26:27], v[42:43], v[74:75]
	v_pk_fma_f32 v[24:25], v[24:25], v[40:41], v[72:73]
	v_cvt_f16_f32_e32 v26, v26
	v_cvt_f16_f32_e32 v24, v24
	v_cvt_f16_f32_sdwa v25, v25 dst_sel:WORD_1 dst_unused:UNUSED_PAD src0_sel:DWORD
	v_cvt_f16_f32_sdwa v27, v27 dst_sel:WORD_1 dst_unused:UNUSED_PAD src0_sel:DWORD
	v_pk_fma_f32 v[22:23], v[22:23], v[42:43], v[74:75]
	v_pk_fma_f32 v[20:21], v[20:21], v[40:41], v[72:73]
	v_or_b32_e32 v24, v25, v24
	v_or_b32_e32 v25, v27, v26
	v_lshl_add_u64 v[26:27], v[2:3], 1, s[64:65]
	global_store_dwordx2 v[26:27], v[24:25], off
	v_sub_f32_e32 v25, v91, v140
	v_sub_f32_e32 v24, v90, v140
	v_sub_f32_e32 v27, v89, v140
	v_sub_f32_e32 v26, v88, v140
	v_pk_mul_f32 v[26:27], v[140:141], v[26:27] op_sel:[1,0]
	v_pk_mul_f32 v[24:25], v[140:141], v[24:25] op_sel:[1,0]
	v_cvt_f16_f32_e32 v20, v20
	v_cvt_f16_f32_sdwa v21, v21 dst_sel:WORD_1 dst_unused:UNUSED_PAD src0_sel:DWORD
	v_cvt_f16_f32_e32 v22, v22
	v_cvt_f16_f32_sdwa v23, v23 dst_sel:WORD_1 dst_unused:UNUSED_PAD src0_sel:DWORD
	v_pk_fma_f32 v[24:25], v[24:25], v[42:43], v[74:75]
	v_pk_fma_f32 v[26:27], v[26:27], v[40:41], v[72:73]
	v_cvt_f16_f32_e32 v24, v24
	v_cvt_f16_f32_e32 v26, v26
	v_cvt_f16_f32_sdwa v27, v27 dst_sel:WORD_1 dst_unused:UNUSED_PAD src0_sel:DWORD
	v_cvt_f16_f32_sdwa v25, v25 dst_sel:WORD_1 dst_unused:UNUSED_PAD src0_sel:DWORD
	v_add_u32_e32 v2, v39, v187
	v_or_b32_e32 v20, v21, v20
	v_or_b32_e32 v21, v23, v22
	v_lshl_add_u64 v[22:23], v[2:3], 1, s[64:65]
	global_store_dwordx2 v[22:23], v[20:21], off
	v_or_b32_e32 v20, v27, v26
	v_or_b32_e32 v21, v25, v24
	v_sub_f32_e32 v25, v87, v142
	v_sub_f32_e32 v24, v86, v142
	v_sub_f32_e32 v27, v85, v142
	v_sub_f32_e32 v26, v84, v142
	v_pk_mul_f32 v[26:27], v[142:143], v[26:27] op_sel:[1,0]
	v_pk_mul_f32 v[24:25], v[142:143], v[24:25] op_sel:[1,0]
	v_pk_fma_f32 v[26:27], v[26:27], v[40:41], v[72:73]
	v_pk_fma_f32 v[24:25], v[24:25], v[42:43], v[74:75]
	v_cvt_f16_f32_e32 v26, v26
	v_cvt_f16_f32_sdwa v27, v27 dst_sel:WORD_1 dst_unused:UNUSED_PAD src0_sel:DWORD
	v_cvt_f16_f32_e32 v24, v24
	v_cvt_f16_f32_sdwa v25, v25 dst_sel:WORD_1 dst_unused:UNUSED_PAD src0_sel:DWORD
	v_add_u32_e32 v2, v39, v186
	v_lshl_add_u64 v[22:23], v[2:3], 1, s[64:65]
	global_store_dwordx2 v[22:23], v[20:21], off
	v_or_b32_e32 v20, v27, v26
	v_or_b32_e32 v21, v25, v24
	v_sub_f32_e32 v25, v127, v136
	v_sub_f32_e32 v24, v126, v136
	v_sub_f32_e32 v27, v125, v136
	v_sub_f32_e32 v26, v124, v136
	v_pk_mul_f32 v[26:27], v[136:137], v[26:27] op_sel:[1,0]
	v_pk_mul_f32 v[24:25], v[136:137], v[24:25] op_sel:[1,0]
	v_pk_fma_f32 v[26:27], v[26:27], v[40:41], v[72:73]
	v_pk_fma_f32 v[24:25], v[24:25], v[42:43], v[74:75]
	v_cvt_f16_f32_e32 v26, v26
	v_cvt_f16_f32_sdwa v27, v27 dst_sel:WORD_1 dst_unused:UNUSED_PAD src0_sel:DWORD
	v_cvt_f16_f32_e32 v24, v24
	v_cvt_f16_f32_sdwa v25, v25 dst_sel:WORD_1 dst_unused:UNUSED_PAD src0_sel:DWORD
	v_add_u32_e32 v2, v39, v185
	v_lshl_add_u64 v[22:23], v[2:3], 1, s[64:65]
	global_store_dwordx2 v[22:23], v[20:21], off
	v_or_b32_e32 v20, v27, v26
	v_or_b32_e32 v21, v25, v24
	v_sub_f32_e32 v25, v119, v138
	v_sub_f32_e32 v24, v118, v138
	v_sub_f32_e32 v27, v117, v138
	v_sub_f32_e32 v26, v116, v138
	v_pk_mul_f32 v[26:27], v[138:139], v[26:27] op_sel:[1,0]
	v_pk_mul_f32 v[24:25], v[138:139], v[24:25] op_sel:[1,0]
	v_pk_fma_f32 v[26:27], v[26:27], v[40:41], v[72:73]
	v_pk_fma_f32 v[24:25], v[24:25], v[42:43], v[74:75]
	v_cvt_f16_f32_e32 v26, v26
	v_cvt_f16_f32_sdwa v27, v27 dst_sel:WORD_1 dst_unused:UNUSED_PAD src0_sel:DWORD
	v_cvt_f16_f32_e32 v24, v24
	v_cvt_f16_f32_sdwa v25, v25 dst_sel:WORD_1 dst_unused:UNUSED_PAD src0_sel:DWORD
	v_add_u32_e32 v2, v39, v157
	v_lshl_add_u64 v[22:23], v[2:3], 1, s[64:65]
	global_store_dwordx2 v[22:23], v[20:21], off
	v_or_b32_e32 v20, v27, v26
	v_or_b32_e32 v21, v25, v24
	v_sub_f32_e32 v25, v79, v132
	v_sub_f32_e32 v24, v78, v132
	v_sub_f32_e32 v27, v77, v132
	v_sub_f32_e32 v26, v76, v132
	v_pk_mul_f32 v[26:27], v[132:133], v[26:27] op_sel:[1,0]
	v_pk_mul_f32 v[24:25], v[132:133], v[24:25] op_sel:[1,0]
	v_pk_fma_f32 v[26:27], v[26:27], v[40:41], v[72:73]
	v_pk_fma_f32 v[24:25], v[24:25], v[42:43], v[74:75]
	v_cvt_f16_f32_e32 v26, v26
	v_cvt_f16_f32_sdwa v27, v27 dst_sel:WORD_1 dst_unused:UNUSED_PAD src0_sel:DWORD
	v_cvt_f16_f32_e32 v24, v24
	v_cvt_f16_f32_sdwa v25, v25 dst_sel:WORD_1 dst_unused:UNUSED_PAD src0_sel:DWORD
	v_add_u32_e32 v2, v39, v36
	v_lshl_add_u64 v[22:23], v[2:3], 1, s[64:65]
	global_store_dwordx2 v[22:23], v[20:21], off
	v_or_b32_e32 v20, v27, v26
	v_or_b32_e32 v21, v25, v24
	v_sub_f32_e32 v25, v71, v134
	v_sub_f32_e32 v24, v70, v134
	v_sub_f32_e32 v27, v69, v134
	v_sub_f32_e32 v26, v68, v134
	v_pk_mul_f32 v[26:27], v[134:135], v[26:27] op_sel:[1,0]
	v_pk_mul_f32 v[24:25], v[134:135], v[24:25] op_sel:[1,0]
	v_pk_fma_f32 v[26:27], v[26:27], v[40:41], v[72:73]
	v_pk_fma_f32 v[24:25], v[24:25], v[42:43], v[74:75]
	v_cvt_f16_f32_e32 v26, v26
	v_cvt_f16_f32_sdwa v27, v27 dst_sel:WORD_1 dst_unused:UNUSED_PAD src0_sel:DWORD
	v_cvt_f16_f32_e32 v24, v24
	v_cvt_f16_f32_sdwa v25, v25 dst_sel:WORD_1 dst_unused:UNUSED_PAD src0_sel:DWORD
	v_add_u32_e32 v2, v39, v37
	v_lshl_add_u64 v[22:23], v[2:3], 1, s[64:65]
	v_add_u32_e32 v2, v39, v38
	global_store_dwordx2 v[22:23], v[20:21], off
	v_or_b32_e32 v20, v27, v26
	v_or_b32_e32 v21, v25, v24
	v_lshl_add_u64 v[22:23], v[2:3], 1, s[64:65]
	global_store_dwordx2 v[22:23], v[20:21], off
	s_nop 1
	v_mov_b32_e32 v20, v208
	v_mov_b32_e32 v21, v209
	v_mov_b32_e32 v22, v210
	v_mov_b32_e32 v23, v211
	s_nop 0
	s_nop 1
	v_mov_b32_e32 v24, v212
	v_mov_b32_e32 v25, v213
	v_mov_b32_e32 v26, v214
	v_mov_b32_e32 v27, v215
	v_or_b32_e32 v39, 0x80, v183
	v_add_u32_e32 v2, v39, v184
	v_pk_fma_f32 v[18:19], v[18:19], v[22:23], v[26:27]
	v_pk_fma_f32 v[16:17], v[16:17], v[20:21], v[24:25]
	v_cvt_f16_f32_e32 v18, v18
	v_cvt_f16_f32_e32 v16, v16
	v_cvt_f16_f32_sdwa v17, v17 dst_sel:WORD_1 dst_unused:UNUSED_PAD src0_sel:DWORD
	v_cvt_f16_f32_sdwa v19, v19 dst_sel:WORD_1 dst_unused:UNUSED_PAD src0_sel:DWORD
	v_pk_fma_f32 v[14:15], v[14:15], v[22:23], v[26:27]
	v_pk_fma_f32 v[12:13], v[12:13], v[20:21], v[24:25]
	v_or_b32_e32 v16, v17, v16
	v_or_b32_e32 v17, v19, v18
	v_lshl_add_u64 v[18:19], v[2:3], 1, s[64:65]
	global_store_dwordx2 v[18:19], v[16:17], off
	v_sub_f32_e32 v17, v55, v140
	v_sub_f32_e32 v16, v54, v140
	v_sub_f32_e32 v19, v53, v140
	v_sub_f32_e32 v18, v52, v140
	v_pk_mul_f32 v[18:19], v[140:141], v[18:19] op_sel:[1,0]
	v_pk_mul_f32 v[16:17], v[140:141], v[16:17] op_sel:[1,0]
	v_cvt_f16_f32_e32 v12, v12
	v_cvt_f16_f32_sdwa v13, v13 dst_sel:WORD_1 dst_unused:UNUSED_PAD src0_sel:DWORD
	v_cvt_f16_f32_e32 v14, v14
	v_cvt_f16_f32_sdwa v15, v15 dst_sel:WORD_1 dst_unused:UNUSED_PAD src0_sel:DWORD
	v_pk_fma_f32 v[16:17], v[16:17], v[22:23], v[26:27]
	v_pk_fma_f32 v[18:19], v[18:19], v[20:21], v[24:25]
	v_cvt_f16_f32_e32 v16, v16
	v_cvt_f16_f32_e32 v18, v18
	v_cvt_f16_f32_sdwa v19, v19 dst_sel:WORD_1 dst_unused:UNUSED_PAD src0_sel:DWORD
	v_cvt_f16_f32_sdwa v17, v17 dst_sel:WORD_1 dst_unused:UNUSED_PAD src0_sel:DWORD
	v_add_u32_e32 v2, v39, v187
	v_or_b32_e32 v12, v13, v12
	v_or_b32_e32 v13, v15, v14
	v_lshl_add_u64 v[14:15], v[2:3], 1, s[64:65]
	global_store_dwordx2 v[14:15], v[12:13], off
	v_or_b32_e32 v12, v19, v18
	v_or_b32_e32 v13, v17, v16
	v_sub_f32_e32 v17, v51, v142
	v_sub_f32_e32 v16, v50, v142
	v_sub_f32_e32 v19, v49, v142
	v_sub_f32_e32 v18, v48, v142
	v_pk_mul_f32 v[18:19], v[142:143], v[18:19] op_sel:[1,0]
	v_pk_mul_f32 v[16:17], v[142:143], v[16:17] op_sel:[1,0]
	v_pk_fma_f32 v[18:19], v[18:19], v[20:21], v[24:25]
	v_pk_fma_f32 v[16:17], v[16:17], v[22:23], v[26:27]
	v_cvt_f16_f32_e32 v18, v18
	v_cvt_f16_f32_sdwa v19, v19 dst_sel:WORD_1 dst_unused:UNUSED_PAD src0_sel:DWORD
	v_cvt_f16_f32_e32 v16, v16
	v_cvt_f16_f32_sdwa v17, v17 dst_sel:WORD_1 dst_unused:UNUSED_PAD src0_sel:DWORD
	v_add_u32_e32 v2, v39, v186
	v_lshl_add_u64 v[14:15], v[2:3], 1, s[64:65]
	global_store_dwordx2 v[14:15], v[12:13], off
	v_or_b32_e32 v12, v19, v18
	v_or_b32_e32 v13, v17, v16
	v_sub_f32_e32 v17, v115, v136
	v_sub_f32_e32 v16, v114, v136
	v_sub_f32_e32 v19, v113, v136
	v_sub_f32_e32 v18, v112, v136
	v_pk_mul_f32 v[18:19], v[136:137], v[18:19] op_sel:[1,0]
	v_pk_mul_f32 v[16:17], v[136:137], v[16:17] op_sel:[1,0]
	v_pk_fma_f32 v[18:19], v[18:19], v[20:21], v[24:25]
	v_pk_fma_f32 v[16:17], v[16:17], v[22:23], v[26:27]
	v_cvt_f16_f32_e32 v18, v18
	v_cvt_f16_f32_sdwa v19, v19 dst_sel:WORD_1 dst_unused:UNUSED_PAD src0_sel:DWORD
	v_cvt_f16_f32_e32 v16, v16
	v_cvt_f16_f32_sdwa v17, v17 dst_sel:WORD_1 dst_unused:UNUSED_PAD src0_sel:DWORD
	v_add_u32_e32 v2, v39, v185
	v_lshl_add_u64 v[14:15], v[2:3], 1, s[64:65]
	global_store_dwordx2 v[14:15], v[12:13], off
	v_or_b32_e32 v12, v19, v18
	v_or_b32_e32 v13, v17, v16
	v_sub_f32_e32 v17, v111, v138
	v_sub_f32_e32 v16, v110, v138
	v_sub_f32_e32 v19, v109, v138
	v_sub_f32_e32 v18, v108, v138
	v_pk_mul_f32 v[18:19], v[138:139], v[18:19] op_sel:[1,0]
	v_pk_mul_f32 v[16:17], v[138:139], v[16:17] op_sel:[1,0]
	v_pk_fma_f32 v[18:19], v[18:19], v[20:21], v[24:25]
	v_pk_fma_f32 v[16:17], v[16:17], v[22:23], v[26:27]
	v_cvt_f16_f32_e32 v18, v18
	v_cvt_f16_f32_sdwa v19, v19 dst_sel:WORD_1 dst_unused:UNUSED_PAD src0_sel:DWORD
	v_cvt_f16_f32_e32 v16, v16
	v_cvt_f16_f32_sdwa v17, v17 dst_sel:WORD_1 dst_unused:UNUSED_PAD src0_sel:DWORD
	v_add_u32_e32 v2, v39, v157
	v_lshl_add_u64 v[14:15], v[2:3], 1, s[64:65]
	global_store_dwordx2 v[14:15], v[12:13], off
	v_or_b32_e32 v12, v19, v18
	v_or_b32_e32 v13, v17, v16
	v_sub_f32_e32 v17, v67, v132
	v_sub_f32_e32 v16, v66, v132
	v_sub_f32_e32 v19, v65, v132
	v_sub_f32_e32 v18, v64, v132
	v_pk_mul_f32 v[18:19], v[132:133], v[18:19] op_sel:[1,0]
	v_pk_mul_f32 v[16:17], v[132:133], v[16:17] op_sel:[1,0]
	v_pk_fma_f32 v[18:19], v[18:19], v[20:21], v[24:25]
	v_pk_fma_f32 v[16:17], v[16:17], v[22:23], v[26:27]
	v_cvt_f16_f32_e32 v18, v18
	v_cvt_f16_f32_sdwa v19, v19 dst_sel:WORD_1 dst_unused:UNUSED_PAD src0_sel:DWORD
	v_cvt_f16_f32_e32 v16, v16
	v_cvt_f16_f32_sdwa v17, v17 dst_sel:WORD_1 dst_unused:UNUSED_PAD src0_sel:DWORD
	v_add_u32_e32 v2, v39, v36
	v_lshl_add_u64 v[14:15], v[2:3], 1, s[64:65]
	global_store_dwordx2 v[14:15], v[12:13], off
	v_or_b32_e32 v12, v19, v18
	v_or_b32_e32 v13, v17, v16
	v_sub_f32_e32 v17, v59, v134
	v_sub_f32_e32 v16, v58, v134
	v_sub_f32_e32 v19, v57, v134
	v_sub_f32_e32 v18, v56, v134
	v_pk_mul_f32 v[18:19], v[134:135], v[18:19] op_sel:[1,0]
	v_pk_mul_f32 v[16:17], v[134:135], v[16:17] op_sel:[1,0]
	v_pk_fma_f32 v[18:19], v[18:19], v[20:21], v[24:25]
	v_pk_fma_f32 v[16:17], v[16:17], v[22:23], v[26:27]
	v_cvt_f16_f32_e32 v18, v18
	v_cvt_f16_f32_sdwa v19, v19 dst_sel:WORD_1 dst_unused:UNUSED_PAD src0_sel:DWORD
	v_cvt_f16_f32_e32 v16, v16
	v_cvt_f16_f32_sdwa v17, v17 dst_sel:WORD_1 dst_unused:UNUSED_PAD src0_sel:DWORD
	v_add_u32_e32 v2, v39, v37
	v_lshl_add_u64 v[14:15], v[2:3], 1, s[64:65]
	v_add_u32_e32 v2, v39, v38
	global_store_dwordx2 v[14:15], v[12:13], off
	v_or_b32_e32 v12, v19, v18
	v_or_b32_e32 v13, v17, v16
	v_lshl_add_u64 v[14:15], v[2:3], 1, s[64:65]
	global_store_dwordx2 v[14:15], v[12:13], off
	s_nop 1
	v_mov_b32_e32 v12, v216
	v_mov_b32_e32 v13, v217
	v_mov_b32_e32 v14, v218
	v_mov_b32_e32 v15, v219
	s_nop 0
	s_nop 1
	v_mov_b32_e32 v16, v220
	v_mov_b32_e32 v17, v221
	v_mov_b32_e32 v18, v222
	v_mov_b32_e32 v19, v223
	v_sub_f32_e32 v1, v11, v144
	v_sub_f32_e32 v0, v10, v144
	v_pk_mul_f32 v[0:1], v[144:145], v[0:1] op_sel:[1,0]
	v_or_b32_e32 v11, 0x90, v183
	v_add_u32_e32 v2, v11, v184
	v_pk_fma_f32 v[0:1], v[0:1], v[14:15], v[18:19]
	v_pk_fma_f32 v[8:9], v[8:9], v[12:13], v[16:17]
	v_cvt_f16_f32_e32 v10, v0
	v_cvt_f16_f32_e32 v8, v8
	v_cvt_f16_f32_sdwa v9, v9 dst_sel:WORD_1 dst_unused:UNUSED_PAD src0_sel:DWORD
	v_cvt_f16_f32_sdwa v1, v1 dst_sel:WORD_1 dst_unused:UNUSED_PAD src0_sel:DWORD
	v_pk_fma_f32 v[6:7], v[6:7], v[14:15], v[18:19]
	v_pk_fma_f32 v[4:5], v[4:5], v[12:13], v[16:17]
	v_cvt_f16_f32_e32 v6, v6
	v_cvt_f16_f32_sdwa v7, v7 dst_sel:WORD_1 dst_unused:UNUSED_PAD src0_sel:DWORD
	v_or_b32_e32 v0, v9, v8
	v_or_b32_e32 v1, v1, v10
	v_lshl_add_u64 v[8:9], v[2:3], 1, s[64:65]
	global_store_dwordx2 v[8:9], v[0:1], off
	v_or_b32_e32 v1, v7, v6
	v_sub_f32_e32 v7, v35, v140
	v_sub_f32_e32 v6, v34, v140
	v_sub_f32_e32 v9, v33, v140
	v_sub_f32_e32 v8, v32, v140
	v_pk_mul_f32 v[8:9], v[140:141], v[8:9] op_sel:[1,0]
	v_pk_mul_f32 v[6:7], v[140:141], v[6:7] op_sel:[1,0]
	v_cvt_f16_f32_e32 v4, v4
	v_cvt_f16_f32_sdwa v5, v5 dst_sel:WORD_1 dst_unused:UNUSED_PAD src0_sel:DWORD
	v_pk_fma_f32 v[6:7], v[6:7], v[14:15], v[18:19]
	v_pk_fma_f32 v[8:9], v[8:9], v[12:13], v[16:17]
	v_cvt_f16_f32_e32 v6, v6
	v_cvt_f16_f32_e32 v8, v8
	v_cvt_f16_f32_sdwa v9, v9 dst_sel:WORD_1 dst_unused:UNUSED_PAD src0_sel:DWORD
	v_cvt_f16_f32_sdwa v7, v7 dst_sel:WORD_1 dst_unused:UNUSED_PAD src0_sel:DWORD
	v_add_u32_e32 v2, v11, v187
	v_or_b32_e32 v0, v5, v4
	v_lshl_add_u64 v[4:5], v[2:3], 1, s[64:65]
	global_store_dwordx2 v[4:5], v[0:1], off
	v_or_b32_e32 v0, v9, v8
	v_or_b32_e32 v1, v7, v6
	v_sub_f32_e32 v7, v31, v142
	v_sub_f32_e32 v6, v30, v142
	v_sub_f32_e32 v9, v29, v142
	v_sub_f32_e32 v8, v28, v142
	v_pk_mul_f32 v[8:9], v[142:143], v[8:9] op_sel:[1,0]
	v_pk_mul_f32 v[6:7], v[142:143], v[6:7] op_sel:[1,0]
	v_pk_fma_f32 v[8:9], v[8:9], v[12:13], v[16:17]
	v_pk_fma_f32 v[6:7], v[6:7], v[14:15], v[18:19]
	v_cvt_f16_f32_e32 v8, v8
	v_cvt_f16_f32_sdwa v9, v9 dst_sel:WORD_1 dst_unused:UNUSED_PAD src0_sel:DWORD
	v_cvt_f16_f32_e32 v6, v6
	v_cvt_f16_f32_sdwa v7, v7 dst_sel:WORD_1 dst_unused:UNUSED_PAD src0_sel:DWORD
	v_add_u32_e32 v2, v11, v186
	v_lshl_add_u64 v[4:5], v[2:3], 1, s[64:65]
	global_store_dwordx2 v[4:5], v[0:1], off
	v_or_b32_e32 v0, v9, v8
	v_or_b32_e32 v1, v7, v6
	v_sub_f32_e32 v7, v99, v136
	v_sub_f32_e32 v6, v98, v136
	v_sub_f32_e32 v9, v97, v136
	v_sub_f32_e32 v8, v96, v136
	v_pk_mul_f32 v[8:9], v[136:137], v[8:9] op_sel:[1,0]
	v_pk_mul_f32 v[6:7], v[136:137], v[6:7] op_sel:[1,0]
	v_pk_fma_f32 v[8:9], v[8:9], v[12:13], v[16:17]
	v_pk_fma_f32 v[6:7], v[6:7], v[14:15], v[18:19]
	v_cvt_f16_f32_e32 v8, v8
	v_cvt_f16_f32_sdwa v9, v9 dst_sel:WORD_1 dst_unused:UNUSED_PAD src0_sel:DWORD
	v_cvt_f16_f32_e32 v6, v6
	v_cvt_f16_f32_sdwa v7, v7 dst_sel:WORD_1 dst_unused:UNUSED_PAD src0_sel:DWORD
	v_add_u32_e32 v2, v11, v185
	v_lshl_add_u64 v[4:5], v[2:3], 1, s[64:65]
	global_store_dwordx2 v[4:5], v[0:1], off
	v_or_b32_e32 v0, v9, v8
	v_or_b32_e32 v1, v7, v6
	v_sub_f32_e32 v7, v95, v138
	v_sub_f32_e32 v6, v94, v138
	v_sub_f32_e32 v9, v93, v138
	v_sub_f32_e32 v8, v92, v138
	v_pk_mul_f32 v[8:9], v[138:139], v[8:9] op_sel:[1,0]
	v_pk_mul_f32 v[6:7], v[138:139], v[6:7] op_sel:[1,0]
	v_pk_fma_f32 v[8:9], v[8:9], v[12:13], v[16:17]
	v_pk_fma_f32 v[6:7], v[6:7], v[14:15], v[18:19]
	v_cvt_f16_f32_e32 v8, v8
	v_cvt_f16_f32_sdwa v9, v9 dst_sel:WORD_1 dst_unused:UNUSED_PAD src0_sel:DWORD
	v_cvt_f16_f32_e32 v6, v6
	v_cvt_f16_f32_sdwa v7, v7 dst_sel:WORD_1 dst_unused:UNUSED_PAD src0_sel:DWORD
	v_add_u32_e32 v2, v11, v157
	v_lshl_add_u64 v[4:5], v[2:3], 1, s[64:65]
	global_store_dwordx2 v[4:5], v[0:1], off
	v_or_b32_e32 v0, v9, v8
	v_or_b32_e32 v1, v7, v6
	v_sub_f32_e32 v7, v63, v132
	v_sub_f32_e32 v6, v62, v132
	v_sub_f32_e32 v9, v61, v132
	v_sub_f32_e32 v8, v60, v132
	v_pk_mul_f32 v[8:9], v[132:133], v[8:9] op_sel:[1,0]
	v_pk_mul_f32 v[6:7], v[132:133], v[6:7] op_sel:[1,0]
	v_pk_fma_f32 v[8:9], v[8:9], v[12:13], v[16:17]
	v_pk_fma_f32 v[6:7], v[6:7], v[14:15], v[18:19]
	v_cvt_f16_f32_e32 v8, v8
	v_cvt_f16_f32_sdwa v9, v9 dst_sel:WORD_1 dst_unused:UNUSED_PAD src0_sel:DWORD
	v_cvt_f16_f32_e32 v6, v6
	v_cvt_f16_f32_sdwa v7, v7 dst_sel:WORD_1 dst_unused:UNUSED_PAD src0_sel:DWORD
	v_add_u32_e32 v2, v11, v36
	v_lshl_add_u64 v[4:5], v[2:3], 1, s[64:65]
	global_store_dwordx2 v[4:5], v[0:1], off
	v_or_b32_e32 v0, v9, v8
	v_or_b32_e32 v1, v7, v6
	v_sub_f32_e32 v7, v47, v134
	v_sub_f32_e32 v6, v46, v134
	v_sub_f32_e32 v9, v45, v134
	v_sub_f32_e32 v8, v44, v134
	v_pk_mul_f32 v[8:9], v[134:135], v[8:9] op_sel:[1,0]
	v_pk_mul_f32 v[6:7], v[134:135], v[6:7] op_sel:[1,0]
	v_pk_fma_f32 v[8:9], v[8:9], v[12:13], v[16:17]
	v_pk_fma_f32 v[6:7], v[6:7], v[14:15], v[18:19]
	v_cvt_f16_f32_e32 v8, v8
	v_cvt_f16_f32_sdwa v9, v9 dst_sel:WORD_1 dst_unused:UNUSED_PAD src0_sel:DWORD
	v_cvt_f16_f32_e32 v6, v6
	v_cvt_f16_f32_sdwa v7, v7 dst_sel:WORD_1 dst_unused:UNUSED_PAD src0_sel:DWORD
	v_add_u32_e32 v2, v11, v37
	v_lshl_add_u64 v[4:5], v[2:3], 1, s[64:65]
	v_add_u32_e32 v2, v11, v38
	global_store_dwordx2 v[4:5], v[0:1], off
	v_or_b32_e32 v0, v9, v8
	v_or_b32_e32 v1, v7, v6
	v_lshl_add_u64 v[4:5], v[2:3], 1, s[64:65]
	global_store_dwordx2 v[4:5], v[0:1], off
